# adds hand-scheduled exact-erf gelu + row sum-of-squares epilogue path for the gMLP input GEMM (same A-S 7.1.26 formula, f32, two element pairs interleaved, no hazard nops)
# speedup vs baseline: 1.0186x; 1.0186x over previous
.LBB0_245:
	s_mov_b32 s2, 1
	v_writelane_b32 v246, s2, 42
	s_cmp_lg_u32 s95, 1
	s_cbranch_scc1 .Lepi_notgelu
	s_and_b64 vcc, exec, s[24:25]
	s_cbranch_vccnz .Lepi_notgelu
	s_and_b64 vcc, exec, s[26:27]
	s_cbranch_vccz .Lepi_notgelu
	v_mov_b32_e32 v196, 0x3e6d3388
	v_mov_b32_e32 v197, 0x3e6d3388
	v_mov_b32_e32 v198, 0x3f07dc22
	v_mov_b32_e32 v199, 0x3f07dc22
	v_mov_b32_e32 v200, 0xbf3a00e3
	v_mov_b32_e32 v201, 0xbf3a00e3
	v_mov_b32_e32 v202, 0x3f35f0e3
	v_mov_b32_e32 v203, 0x3f35f0e3
	v_mov_b32_e32 v210, 0xbe11a98e
	v_mov_b32_e32 v211, 0xbe11a98e
	v_mov_b32_e32 v212, 0x3e027906
	v_mov_b32_e32 v213, 0x3e027906
	v_mov_b32_e32 v214, 0xbf38aa3b
	v_mov_b32_e32 v215, 0xbf38aa3b
	v_lshl_add_u32 v216, s6, 8, v163
	s_lshl_b32 s2, s18, 8
	s_or_b32 s2, s2, s38
	v_or_b32_e32 v217, s2, v137
	v_mov_b32_e32 v236, v216
	v_mul_lo_u32 v216, v216, s33
	v_add_lshl_u32 v216, v216, v217, 1
	v_fma_f32 v144, |v124|, v196, 1.0
	v_fma_f32 v145, |v125|, v196, 1.0
	v_fma_f32 v152, |v126|, v196, 1.0
	v_fma_f32 v153, |v127|, v196, 1.0
	v_pk_mul_f32 v[146:147], v[124:125], v[124:125]
	v_pk_mul_f32 v[154:155], v[126:127], v[126:127]
	v_rcp_f32_e32 v144, v144
	v_rcp_f32_e32 v145, v145
	v_rcp_f32_e32 v152, v152
	v_rcp_f32_e32 v153, v153
	v_pk_mul_f32 v[146:147], v[146:147], v[214:215]
	v_pk_mul_f32 v[154:155], v[154:155], v[214:215]
	v_exp_f32_e32 v146, v146
	v_exp_f32_e32 v147, v147
	v_exp_f32_e32 v154, v154
	v_exp_f32_e32 v155, v155
	v_pk_fma_f32 v[148:149], v[144:145], v[198:199], v[200:201]
	v_pk_fma_f32 v[156:157], v[152:153], v[198:199], v[200:201]
	v_pk_fma_f32 v[148:149], v[148:149], v[144:145], v[202:203]
	v_pk_fma_f32 v[156:157], v[156:157], v[152:153], v[202:203]
	v_pk_fma_f32 v[148:149], v[148:149], v[144:145], v[210:211]
	v_pk_fma_f32 v[156:157], v[156:157], v[152:153], v[210:211]
	v_pk_fma_f32 v[148:149], v[148:149], v[144:145], v[212:213]
	v_pk_fma_f32 v[156:157], v[156:157], v[152:153], v[212:213]
	v_pk_mul_f32 v[148:149], v[148:149], v[144:145]
	v_pk_mul_f32 v[156:157], v[156:157], v[152:153]
	v_max_f32_e32 v150, 0, v124
	v_max_f32_e32 v151, 0, v125
	v_max_f32_e32 v166, 0, v126
	v_max_f32_e32 v167, 0, v127
	v_pk_mul_f32 v[148:149], v[148:149], v[146:147]
	v_pk_mul_f32 v[156:157], v[156:157], v[154:155]
	v_fma_f32 v124, -|v124|, v148, v150
	v_fma_f32 v125, -|v125|, v149, v151
	v_fma_f32 v126, -|v126|, v156, v166
	v_fma_f32 v127, -|v127|, v157, v167
	v_pk_mul_f32 v[226:227], v[124:125], v[124:125]
	v_pk_fma_f32 v[226:227], v[126:127], v[126:127], v[226:227]
	v_cvt_pk_bf16_f32 v168, v124, v125
	v_cvt_pk_bf16_f32 v169, v126, v127
	v_fma_f32 v144, |v120|, v196, 1.0
	v_fma_f32 v145, |v121|, v196, 1.0
	v_fma_f32 v152, |v122|, v196, 1.0
	v_fma_f32 v153, |v123|, v196, 1.0
	v_pk_mul_f32 v[146:147], v[120:121], v[120:121]
	v_pk_mul_f32 v[154:155], v[122:123], v[122:123]
	v_rcp_f32_e32 v144, v144
	v_rcp_f32_e32 v145, v145
	v_rcp_f32_e32 v152, v152
	v_rcp_f32_e32 v153, v153
	v_pk_mul_f32 v[146:147], v[146:147], v[214:215]
	v_pk_mul_f32 v[154:155], v[154:155], v[214:215]
	v_exp_f32_e32 v146, v146
	v_exp_f32_e32 v147, v147
	v_exp_f32_e32 v154, v154
	v_exp_f32_e32 v155, v155
	v_pk_fma_f32 v[148:149], v[144:145], v[198:199], v[200:201]
	v_pk_fma_f32 v[156:157], v[152:153], v[198:199], v[200:201]
	v_pk_fma_f32 v[148:149], v[148:149], v[144:145], v[202:203]
	v_pk_fma_f32 v[156:157], v[156:157], v[152:153], v[202:203]
	v_pk_fma_f32 v[148:149], v[148:149], v[144:145], v[210:211]
	v_pk_fma_f32 v[156:157], v[156:157], v[152:153], v[210:211]
	v_pk_fma_f32 v[148:149], v[148:149], v[144:145], v[212:213]
	v_pk_fma_f32 v[156:157], v[156:157], v[152:153], v[212:213]
	v_pk_mul_f32 v[148:149], v[148:149], v[144:145]
	v_pk_mul_f32 v[156:157], v[156:157], v[152:153]
	v_max_f32_e32 v150, 0, v120
	v_max_f32_e32 v151, 0, v121
	v_max_f32_e32 v166, 0, v122
	v_max_f32_e32 v167, 0, v123
	v_pk_mul_f32 v[148:149], v[148:149], v[146:147]
	v_pk_mul_f32 v[156:157], v[156:157], v[154:155]
	v_fma_f32 v120, -|v120|, v148, v150
	v_fma_f32 v121, -|v121|, v149, v151
	v_fma_f32 v122, -|v122|, v156, v166
	v_fma_f32 v123, -|v123|, v157, v167
	v_pk_fma_f32 v[226:227], v[120:121], v[120:121], v[226:227]
	v_pk_fma_f32 v[226:227], v[122:123], v[122:123], v[226:227]
	v_cvt_pk_bf16_f32 v170, v120, v121
	v_cvt_pk_bf16_f32 v171, v122, v123
	buffer_store_dwordx4 v[168:171], v216, s[72:75], 0 offen
	v_fma_f32 v144, |v116|, v196, 1.0
	v_fma_f32 v145, |v117|, v196, 1.0
	v_fma_f32 v152, |v118|, v196, 1.0
	v_fma_f32 v153, |v119|, v196, 1.0
	v_pk_mul_f32 v[146:147], v[116:117], v[116:117]
	v_pk_mul_f32 v[154:155], v[118:119], v[118:119]
	v_rcp_f32_e32 v144, v144
	v_rcp_f32_e32 v145, v145
	v_rcp_f32_e32 v152, v152
	v_rcp_f32_e32 v153, v153
	v_pk_mul_f32 v[146:147], v[146:147], v[214:215]
	v_pk_mul_f32 v[154:155], v[154:155], v[214:215]
	v_exp_f32_e32 v146, v146
	v_exp_f32_e32 v147, v147
	v_exp_f32_e32 v154, v154
	v_exp_f32_e32 v155, v155
	v_pk_fma_f32 v[148:149], v[144:145], v[198:199], v[200:201]
	v_pk_fma_f32 v[156:157], v[152:153], v[198:199], v[200:201]
	v_pk_fma_f32 v[148:149], v[148:149], v[144:145], v[202:203]
	v_pk_fma_f32 v[156:157], v[156:157], v[152:153], v[202:203]
	v_pk_fma_f32 v[148:149], v[148:149], v[144:145], v[210:211]
	v_pk_fma_f32 v[156:157], v[156:157], v[152:153], v[210:211]
	v_pk_fma_f32 v[148:149], v[148:149], v[144:145], v[212:213]
	v_pk_fma_f32 v[156:157], v[156:157], v[152:153], v[212:213]
	v_pk_mul_f32 v[148:149], v[148:149], v[144:145]
	v_pk_mul_f32 v[156:157], v[156:157], v[152:153]
	v_max_f32_e32 v150, 0, v116
	v_max_f32_e32 v151, 0, v117
	v_max_f32_e32 v166, 0, v118
	v_max_f32_e32 v167, 0, v119
	v_pk_mul_f32 v[148:149], v[148:149], v[146:147]
	v_pk_mul_f32 v[156:157], v[156:157], v[154:155]
	v_fma_f32 v116, -|v116|, v148, v150
	v_fma_f32 v117, -|v117|, v149, v151
	v_fma_f32 v118, -|v118|, v156, v166
	v_fma_f32 v119, -|v119|, v157, v167
	v_pk_fma_f32 v[226:227], v[116:117], v[116:117], v[226:227]
	v_pk_fma_f32 v[226:227], v[118:119], v[118:119], v[226:227]
	v_cvt_pk_bf16_f32 v232, v116, v117
	v_cvt_pk_bf16_f32 v233, v118, v119
	v_fma_f32 v144, |v112|, v196, 1.0
	v_fma_f32 v145, |v113|, v196, 1.0
	v_fma_f32 v152, |v114|, v196, 1.0
	v_fma_f32 v153, |v115|, v196, 1.0
	v_pk_mul_f32 v[146:147], v[112:113], v[112:113]
	v_pk_mul_f32 v[154:155], v[114:115], v[114:115]
	v_rcp_f32_e32 v144, v144
	v_rcp_f32_e32 v145, v145
	v_rcp_f32_e32 v152, v152
	v_rcp_f32_e32 v153, v153
	v_pk_mul_f32 v[146:147], v[146:147], v[214:215]
	v_pk_mul_f32 v[154:155], v[154:155], v[214:215]
	v_exp_f32_e32 v146, v146
	v_exp_f32_e32 v147, v147
	v_exp_f32_e32 v154, v154
	v_exp_f32_e32 v155, v155
	v_pk_fma_f32 v[148:149], v[144:145], v[198:199], v[200:201]
	v_pk_fma_f32 v[156:157], v[152:153], v[198:199], v[200:201]
	v_pk_fma_f32 v[148:149], v[148:149], v[144:145], v[202:203]
	v_pk_fma_f32 v[156:157], v[156:157], v[152:153], v[202:203]
	v_pk_fma_f32 v[148:149], v[148:149], v[144:145], v[210:211]
	v_pk_fma_f32 v[156:157], v[156:157], v[152:153], v[210:211]
	v_pk_fma_f32 v[148:149], v[148:149], v[144:145], v[212:213]
	v_pk_fma_f32 v[156:157], v[156:157], v[152:153], v[212:213]
	v_pk_mul_f32 v[148:149], v[148:149], v[144:145]
	v_pk_mul_f32 v[156:157], v[156:157], v[152:153]
	v_max_f32_e32 v150, 0, v112
	v_max_f32_e32 v151, 0, v113
	v_max_f32_e32 v166, 0, v114
	v_max_f32_e32 v167, 0, v115
	v_pk_mul_f32 v[148:149], v[148:149], v[146:147]
	v_pk_mul_f32 v[156:157], v[156:157], v[154:155]
	v_fma_f32 v112, -|v112|, v148, v150
	v_fma_f32 v113, -|v113|, v149, v151
	v_fma_f32 v114, -|v114|, v156, v166
	v_fma_f32 v115, -|v115|, v157, v167
	v_pk_fma_f32 v[226:227], v[112:113], v[112:113], v[226:227]
	v_pk_fma_f32 v[226:227], v[114:115], v[114:115], v[226:227]
	v_cvt_pk_bf16_f32 v234, v112, v113
	v_cvt_pk_bf16_f32 v235, v114, v115
	buffer_store_dwordx4 v[232:235], v216, s[72:75], 0 offen offset:256
	v_add_f32_e32 v218, v226, v227
	v_fma_f32 v144, |v108|, v196, 1.0
	v_fma_f32 v145, |v109|, v196, 1.0
	v_fma_f32 v152, |v110|, v196, 1.0
	v_fma_f32 v153, |v111|, v196, 1.0
	v_pk_mul_f32 v[146:147], v[108:109], v[108:109]
	v_pk_mul_f32 v[154:155], v[110:111], v[110:111]
	v_rcp_f32_e32 v144, v144
	v_rcp_f32_e32 v145, v145
	v_rcp_f32_e32 v152, v152
	v_rcp_f32_e32 v153, v153
	v_pk_mul_f32 v[146:147], v[146:147], v[214:215]
	v_pk_mul_f32 v[154:155], v[154:155], v[214:215]
	v_exp_f32_e32 v146, v146
	v_exp_f32_e32 v147, v147
	v_exp_f32_e32 v154, v154
	v_exp_f32_e32 v155, v155
	v_pk_fma_f32 v[148:149], v[144:145], v[198:199], v[200:201]
	v_pk_fma_f32 v[156:157], v[152:153], v[198:199], v[200:201]
	v_pk_fma_f32 v[148:149], v[148:149], v[144:145], v[202:203]
	v_pk_fma_f32 v[156:157], v[156:157], v[152:153], v[202:203]
	v_pk_fma_f32 v[148:149], v[148:149], v[144:145], v[210:211]
	v_pk_fma_f32 v[156:157], v[156:157], v[152:153], v[210:211]
	v_pk_fma_f32 v[148:149], v[148:149], v[144:145], v[212:213]
	v_pk_fma_f32 v[156:157], v[156:157], v[152:153], v[212:213]
	v_pk_mul_f32 v[148:149], v[148:149], v[144:145]
	v_pk_mul_f32 v[156:157], v[156:157], v[152:153]
	v_max_f32_e32 v150, 0, v108
	v_max_f32_e32 v151, 0, v109
	v_max_f32_e32 v166, 0, v110
	v_max_f32_e32 v167, 0, v111
	v_pk_mul_f32 v[148:149], v[148:149], v[146:147]
	v_pk_mul_f32 v[156:157], v[156:157], v[154:155]
	v_fma_f32 v108, -|v108|, v148, v150
	v_fma_f32 v109, -|v109|, v149, v151
	v_fma_f32 v110, -|v110|, v156, v166
	v_fma_f32 v111, -|v111|, v157, v167
	v_pk_mul_f32 v[226:227], v[108:109], v[108:109]
	v_pk_fma_f32 v[226:227], v[110:111], v[110:111], v[226:227]
	v_cvt_pk_bf16_f32 v168, v108, v109
	v_cvt_pk_bf16_f32 v169, v110, v111
	v_fma_f32 v144, |v104|, v196, 1.0
	v_fma_f32 v145, |v105|, v196, 1.0
	v_fma_f32 v152, |v106|, v196, 1.0
	v_fma_f32 v153, |v107|, v196, 1.0
	v_pk_mul_f32 v[146:147], v[104:105], v[104:105]
	v_pk_mul_f32 v[154:155], v[106:107], v[106:107]
	v_rcp_f32_e32 v144, v144
	v_rcp_f32_e32 v145, v145
	v_rcp_f32_e32 v152, v152
	v_rcp_f32_e32 v153, v153
	v_pk_mul_f32 v[146:147], v[146:147], v[214:215]
	v_pk_mul_f32 v[154:155], v[154:155], v[214:215]
	v_exp_f32_e32 v146, v146
	v_exp_f32_e32 v147, v147
	v_exp_f32_e32 v154, v154
	v_exp_f32_e32 v155, v155
	v_pk_fma_f32 v[148:149], v[144:145], v[198:199], v[200:201]
	v_pk_fma_f32 v[156:157], v[152:153], v[198:199], v[200:201]
	v_pk_fma_f32 v[148:149], v[148:149], v[144:145], v[202:203]
	v_pk_fma_f32 v[156:157], v[156:157], v[152:153], v[202:203]
	v_pk_fma_f32 v[148:149], v[148:149], v[144:145], v[210:211]
	v_pk_fma_f32 v[156:157], v[156:157], v[152:153], v[210:211]
	v_pk_fma_f32 v[148:149], v[148:149], v[144:145], v[212:213]
	v_pk_fma_f32 v[156:157], v[156:157], v[152:153], v[212:213]
	v_pk_mul_f32 v[148:149], v[148:149], v[144:145]
	v_pk_mul_f32 v[156:157], v[156:157], v[152:153]
	v_max_f32_e32 v150, 0, v104
	v_max_f32_e32 v151, 0, v105
	v_max_f32_e32 v166, 0, v106
	v_max_f32_e32 v167, 0, v107
	v_pk_mul_f32 v[148:149], v[148:149], v[146:147]
	v_pk_mul_f32 v[156:157], v[156:157], v[154:155]
	v_fma_f32 v104, -|v104|, v148, v150
	v_fma_f32 v105, -|v105|, v149, v151
	v_fma_f32 v106, -|v106|, v156, v166
	v_fma_f32 v107, -|v107|, v157, v167
	v_pk_fma_f32 v[226:227], v[104:105], v[104:105], v[226:227]
	v_pk_fma_f32 v[226:227], v[106:107], v[106:107], v[226:227]
	v_cvt_pk_bf16_f32 v170, v104, v105
	v_cvt_pk_bf16_f32 v171, v106, v107
	s_mul_i32 s2, s33, 0x20
	buffer_store_dwordx4 v[168:171], v216, s[72:75], s2 offen
	v_fma_f32 v144, |v100|, v196, 1.0
	v_fma_f32 v145, |v101|, v196, 1.0
	v_fma_f32 v152, |v102|, v196, 1.0
	v_fma_f32 v153, |v103|, v196, 1.0
	v_pk_mul_f32 v[146:147], v[100:101], v[100:101]
	v_pk_mul_f32 v[154:155], v[102:103], v[102:103]
	v_rcp_f32_e32 v144, v144
	v_rcp_f32_e32 v145, v145
	v_rcp_f32_e32 v152, v152
	v_rcp_f32_e32 v153, v153
	v_pk_mul_f32 v[146:147], v[146:147], v[214:215]
	v_pk_mul_f32 v[154:155], v[154:155], v[214:215]
	v_exp_f32_e32 v146, v146
	v_exp_f32_e32 v147, v147
	v_exp_f32_e32 v154, v154
	v_exp_f32_e32 v155, v155
	v_pk_fma_f32 v[148:149], v[144:145], v[198:199], v[200:201]
	v_pk_fma_f32 v[156:157], v[152:153], v[198:199], v[200:201]
	v_pk_fma_f32 v[148:149], v[148:149], v[144:145], v[202:203]
	v_pk_fma_f32 v[156:157], v[156:157], v[152:153], v[202:203]
	v_pk_fma_f32 v[148:149], v[148:149], v[144:145], v[210:211]
	v_pk_fma_f32 v[156:157], v[156:157], v[152:153], v[210:211]
	v_pk_fma_f32 v[148:149], v[148:149], v[144:145], v[212:213]
	v_pk_fma_f32 v[156:157], v[156:157], v[152:153], v[212:213]
	v_pk_mul_f32 v[148:149], v[148:149], v[144:145]
	v_pk_mul_f32 v[156:157], v[156:157], v[152:153]
	v_max_f32_e32 v150, 0, v100
	v_max_f32_e32 v151, 0, v101
	v_max_f32_e32 v166, 0, v102
	v_max_f32_e32 v167, 0, v103
	v_pk_mul_f32 v[148:149], v[148:149], v[146:147]
	v_pk_mul_f32 v[156:157], v[156:157], v[154:155]
	v_fma_f32 v100, -|v100|, v148, v150
	v_fma_f32 v101, -|v101|, v149, v151
	v_fma_f32 v102, -|v102|, v156, v166
	v_fma_f32 v103, -|v103|, v157, v167
	v_pk_fma_f32 v[226:227], v[100:101], v[100:101], v[226:227]
	v_pk_fma_f32 v[226:227], v[102:103], v[102:103], v[226:227]
	v_cvt_pk_bf16_f32 v232, v100, v101
	v_cvt_pk_bf16_f32 v233, v102, v103
	v_fma_f32 v144, |v96|, v196, 1.0
	v_fma_f32 v145, |v97|, v196, 1.0
	v_fma_f32 v152, |v98|, v196, 1.0
	v_fma_f32 v153, |v99|, v196, 1.0
	v_pk_mul_f32 v[146:147], v[96:97], v[96:97]
	v_pk_mul_f32 v[154:155], v[98:99], v[98:99]
	v_rcp_f32_e32 v144, v144
	v_rcp_f32_e32 v145, v145
	v_rcp_f32_e32 v152, v152
	v_rcp_f32_e32 v153, v153
	v_pk_mul_f32 v[146:147], v[146:147], v[214:215]
	v_pk_mul_f32 v[154:155], v[154:155], v[214:215]
	v_exp_f32_e32 v146, v146
	v_exp_f32_e32 v147, v147
	v_exp_f32_e32 v154, v154
	v_exp_f32_e32 v155, v155
	v_pk_fma_f32 v[148:149], v[144:145], v[198:199], v[200:201]
	v_pk_fma_f32 v[156:157], v[152:153], v[198:199], v[200:201]
	v_pk_fma_f32 v[148:149], v[148:149], v[144:145], v[202:203]
	v_pk_fma_f32 v[156:157], v[156:157], v[152:153], v[202:203]
	v_pk_fma_f32 v[148:149], v[148:149], v[144:145], v[210:211]
	v_pk_fma_f32 v[156:157], v[156:157], v[152:153], v[210:211]
	v_pk_fma_f32 v[148:149], v[148:149], v[144:145], v[212:213]
	v_pk_fma_f32 v[156:157], v[156:157], v[152:153], v[212:213]
	v_pk_mul_f32 v[148:149], v[148:149], v[144:145]
	v_pk_mul_f32 v[156:157], v[156:157], v[152:153]
	v_max_f32_e32 v150, 0, v96
	v_max_f32_e32 v151, 0, v97
	v_max_f32_e32 v166, 0, v98
	v_max_f32_e32 v167, 0, v99
	v_pk_mul_f32 v[148:149], v[148:149], v[146:147]
	v_pk_mul_f32 v[156:157], v[156:157], v[154:155]
	v_fma_f32 v96, -|v96|, v148, v150
	v_fma_f32 v97, -|v97|, v149, v151
	v_fma_f32 v98, -|v98|, v156, v166
	v_fma_f32 v99, -|v99|, v157, v167
	v_pk_fma_f32 v[226:227], v[96:97], v[96:97], v[226:227]
	v_pk_fma_f32 v[226:227], v[98:99], v[98:99], v[226:227]
	v_cvt_pk_bf16_f32 v234, v96, v97
	v_cvt_pk_bf16_f32 v235, v98, v99
	buffer_store_dwordx4 v[232:235], v216, s[72:75], s2 offen offset:256
	v_add_f32_e32 v219, v226, v227
	v_fma_f32 v144, |v92|, v196, 1.0
	v_fma_f32 v145, |v93|, v196, 1.0
	v_fma_f32 v152, |v94|, v196, 1.0
	v_fma_f32 v153, |v95|, v196, 1.0
	v_pk_mul_f32 v[146:147], v[92:93], v[92:93]
	v_pk_mul_f32 v[154:155], v[94:95], v[94:95]
	v_rcp_f32_e32 v144, v144
	v_rcp_f32_e32 v145, v145
	v_rcp_f32_e32 v152, v152
	v_rcp_f32_e32 v153, v153
	v_pk_mul_f32 v[146:147], v[146:147], v[214:215]
	v_pk_mul_f32 v[154:155], v[154:155], v[214:215]
	v_exp_f32_e32 v146, v146
	v_exp_f32_e32 v147, v147
	v_exp_f32_e32 v154, v154
	v_exp_f32_e32 v155, v155
	v_pk_fma_f32 v[148:149], v[144:145], v[198:199], v[200:201]
	v_pk_fma_f32 v[156:157], v[152:153], v[198:199], v[200:201]
	v_pk_fma_f32 v[148:149], v[148:149], v[144:145], v[202:203]
	v_pk_fma_f32 v[156:157], v[156:157], v[152:153], v[202:203]
	v_pk_fma_f32 v[148:149], v[148:149], v[144:145], v[210:211]
	v_pk_fma_f32 v[156:157], v[156:157], v[152:153], v[210:211]
	v_pk_fma_f32 v[148:149], v[148:149], v[144:145], v[212:213]
	v_pk_fma_f32 v[156:157], v[156:157], v[152:153], v[212:213]
	v_pk_mul_f32 v[148:149], v[148:149], v[144:145]
	v_pk_mul_f32 v[156:157], v[156:157], v[152:153]
	v_max_f32_e32 v150, 0, v92
	v_max_f32_e32 v151, 0, v93
	v_max_f32_e32 v166, 0, v94
	v_max_f32_e32 v167, 0, v95
	v_pk_mul_f32 v[148:149], v[148:149], v[146:147]
	v_pk_mul_f32 v[156:157], v[156:157], v[154:155]
	v_fma_f32 v92, -|v92|, v148, v150
	v_fma_f32 v93, -|v93|, v149, v151
	v_fma_f32 v94, -|v94|, v156, v166
	v_fma_f32 v95, -|v95|, v157, v167
	v_pk_mul_f32 v[226:227], v[92:93], v[92:93]
	v_pk_fma_f32 v[226:227], v[94:95], v[94:95], v[226:227]
	v_cvt_pk_bf16_f32 v168, v92, v93
	v_cvt_pk_bf16_f32 v169, v94, v95
	v_fma_f32 v144, |v88|, v196, 1.0
	v_fma_f32 v145, |v89|, v196, 1.0
	v_fma_f32 v152, |v90|, v196, 1.0
	v_fma_f32 v153, |v91|, v196, 1.0
	v_pk_mul_f32 v[146:147], v[88:89], v[88:89]
	v_pk_mul_f32 v[154:155], v[90:91], v[90:91]
	v_rcp_f32_e32 v144, v144
	v_rcp_f32_e32 v145, v145
	v_rcp_f32_e32 v152, v152
	v_rcp_f32_e32 v153, v153
	v_pk_mul_f32 v[146:147], v[146:147], v[214:215]
	v_pk_mul_f32 v[154:155], v[154:155], v[214:215]
	v_exp_f32_e32 v146, v146
	v_exp_f32_e32 v147, v147
	v_exp_f32_e32 v154, v154
	v_exp_f32_e32 v155, v155
	v_pk_fma_f32 v[148:149], v[144:145], v[198:199], v[200:201]
	v_pk_fma_f32 v[156:157], v[152:153], v[198:199], v[200:201]
	v_pk_fma_f32 v[148:149], v[148:149], v[144:145], v[202:203]
	v_pk_fma_f32 v[156:157], v[156:157], v[152:153], v[202:203]
	v_pk_fma_f32 v[148:149], v[148:149], v[144:145], v[210:211]
	v_pk_fma_f32 v[156:157], v[156:157], v[152:153], v[210:211]
	v_pk_fma_f32 v[148:149], v[148:149], v[144:145], v[212:213]
	v_pk_fma_f32 v[156:157], v[156:157], v[152:153], v[212:213]
	v_pk_mul_f32 v[148:149], v[148:149], v[144:145]
	v_pk_mul_f32 v[156:157], v[156:157], v[152:153]
	v_max_f32_e32 v150, 0, v88
	v_max_f32_e32 v151, 0, v89
	v_max_f32_e32 v166, 0, v90
	v_max_f32_e32 v167, 0, v91
	v_pk_mul_f32 v[148:149], v[148:149], v[146:147]
	v_pk_mul_f32 v[156:157], v[156:157], v[154:155]
	v_fma_f32 v88, -|v88|, v148, v150
	v_fma_f32 v89, -|v89|, v149, v151
	v_fma_f32 v90, -|v90|, v156, v166
	v_fma_f32 v91, -|v91|, v157, v167
	v_pk_fma_f32 v[226:227], v[88:89], v[88:89], v[226:227]
	v_pk_fma_f32 v[226:227], v[90:91], v[90:91], v[226:227]
	v_cvt_pk_bf16_f32 v170, v88, v89
	v_cvt_pk_bf16_f32 v171, v90, v91
	s_mul_i32 s2, s33, 0x40
	buffer_store_dwordx4 v[168:171], v216, s[72:75], s2 offen
	v_fma_f32 v144, |v84|, v196, 1.0
	v_fma_f32 v145, |v85|, v196, 1.0
	v_fma_f32 v152, |v86|, v196, 1.0
	v_fma_f32 v153, |v87|, v196, 1.0
	v_pk_mul_f32 v[146:147], v[84:85], v[84:85]
	v_pk_mul_f32 v[154:155], v[86:87], v[86:87]
	v_rcp_f32_e32 v144, v144
	v_rcp_f32_e32 v145, v145
	v_rcp_f32_e32 v152, v152
	v_rcp_f32_e32 v153, v153
	v_pk_mul_f32 v[146:147], v[146:147], v[214:215]
	v_pk_mul_f32 v[154:155], v[154:155], v[214:215]
	v_exp_f32_e32 v146, v146
	v_exp_f32_e32 v147, v147
	v_exp_f32_e32 v154, v154
	v_exp_f32_e32 v155, v155
	v_pk_fma_f32 v[148:149], v[144:145], v[198:199], v[200:201]
	v_pk_fma_f32 v[156:157], v[152:153], v[198:199], v[200:201]
	v_pk_fma_f32 v[148:149], v[148:149], v[144:145], v[202:203]
	v_pk_fma_f32 v[156:157], v[156:157], v[152:153], v[202:203]
	v_pk_fma_f32 v[148:149], v[148:149], v[144:145], v[210:211]
	v_pk_fma_f32 v[156:157], v[156:157], v[152:153], v[210:211]
	v_pk_fma_f32 v[148:149], v[148:149], v[144:145], v[212:213]
	v_pk_fma_f32 v[156:157], v[156:157], v[152:153], v[212:213]
	v_pk_mul_f32 v[148:149], v[148:149], v[144:145]
	v_pk_mul_f32 v[156:157], v[156:157], v[152:153]
	v_max_f32_e32 v150, 0, v84
	v_max_f32_e32 v151, 0, v85
	v_max_f32_e32 v166, 0, v86
	v_max_f32_e32 v167, 0, v87
	v_pk_mul_f32 v[148:149], v[148:149], v[146:147]
	v_pk_mul_f32 v[156:157], v[156:157], v[154:155]
	v_fma_f32 v84, -|v84|, v148, v150
	v_fma_f32 v85, -|v85|, v149, v151
	v_fma_f32 v86, -|v86|, v156, v166
	v_fma_f32 v87, -|v87|, v157, v167
	v_pk_fma_f32 v[226:227], v[84:85], v[84:85], v[226:227]
	v_pk_fma_f32 v[226:227], v[86:87], v[86:87], v[226:227]
	v_cvt_pk_bf16_f32 v232, v84, v85
	v_cvt_pk_bf16_f32 v233, v86, v87
	v_fma_f32 v144, |v80|, v196, 1.0
	v_fma_f32 v145, |v81|, v196, 1.0
	v_fma_f32 v152, |v82|, v196, 1.0
	v_fma_f32 v153, |v83|, v196, 1.0
	v_pk_mul_f32 v[146:147], v[80:81], v[80:81]
	v_pk_mul_f32 v[154:155], v[82:83], v[82:83]
	v_rcp_f32_e32 v144, v144
	v_rcp_f32_e32 v145, v145
	v_rcp_f32_e32 v152, v152
	v_rcp_f32_e32 v153, v153
	v_pk_mul_f32 v[146:147], v[146:147], v[214:215]
	v_pk_mul_f32 v[154:155], v[154:155], v[214:215]
	v_exp_f32_e32 v146, v146
	v_exp_f32_e32 v147, v147
	v_exp_f32_e32 v154, v154
	v_exp_f32_e32 v155, v155
	v_pk_fma_f32 v[148:149], v[144:145], v[198:199], v[200:201]
	v_pk_fma_f32 v[156:157], v[152:153], v[198:199], v[200:201]
	v_pk_fma_f32 v[148:149], v[148:149], v[144:145], v[202:203]
	v_pk_fma_f32 v[156:157], v[156:157], v[152:153], v[202:203]
	v_pk_fma_f32 v[148:149], v[148:149], v[144:145], v[210:211]
	v_pk_fma_f32 v[156:157], v[156:157], v[152:153], v[210:211]
	v_pk_fma_f32 v[148:149], v[148:149], v[144:145], v[212:213]
	v_pk_fma_f32 v[156:157], v[156:157], v[152:153], v[212:213]
	v_pk_mul_f32 v[148:149], v[148:149], v[144:145]
	v_pk_mul_f32 v[156:157], v[156:157], v[152:153]
	v_max_f32_e32 v150, 0, v80
	v_max_f32_e32 v151, 0, v81
	v_max_f32_e32 v166, 0, v82
	v_max_f32_e32 v167, 0, v83
	v_pk_mul_f32 v[148:149], v[148:149], v[146:147]
	v_pk_mul_f32 v[156:157], v[156:157], v[154:155]
	v_fma_f32 v80, -|v80|, v148, v150
	v_fma_f32 v81, -|v81|, v149, v151
	v_fma_f32 v82, -|v82|, v156, v166
	v_fma_f32 v83, -|v83|, v157, v167
	v_pk_fma_f32 v[226:227], v[80:81], v[80:81], v[226:227]
	v_pk_fma_f32 v[226:227], v[82:83], v[82:83], v[226:227]
	v_cvt_pk_bf16_f32 v234, v80, v81
	v_cvt_pk_bf16_f32 v235, v82, v83
	buffer_store_dwordx4 v[232:235], v216, s[72:75], s2 offen offset:256
	v_add_f32_e32 v220, v226, v227
	v_fma_f32 v144, |v76|, v196, 1.0
	v_fma_f32 v145, |v77|, v196, 1.0
	v_fma_f32 v152, |v78|, v196, 1.0
	v_fma_f32 v153, |v79|, v196, 1.0
	v_pk_mul_f32 v[146:147], v[76:77], v[76:77]
	v_pk_mul_f32 v[154:155], v[78:79], v[78:79]
	v_rcp_f32_e32 v144, v144
	v_rcp_f32_e32 v145, v145
	v_rcp_f32_e32 v152, v152
	v_rcp_f32_e32 v153, v153
	v_pk_mul_f32 v[146:147], v[146:147], v[214:215]
	v_pk_mul_f32 v[154:155], v[154:155], v[214:215]
	v_exp_f32_e32 v146, v146
	v_exp_f32_e32 v147, v147
	v_exp_f32_e32 v154, v154
	v_exp_f32_e32 v155, v155
	v_pk_fma_f32 v[148:149], v[144:145], v[198:199], v[200:201]
	v_pk_fma_f32 v[156:157], v[152:153], v[198:199], v[200:201]
	v_pk_fma_f32 v[148:149], v[148:149], v[144:145], v[202:203]
	v_pk_fma_f32 v[156:157], v[156:157], v[152:153], v[202:203]
	v_pk_fma_f32 v[148:149], v[148:149], v[144:145], v[210:211]
	v_pk_fma_f32 v[156:157], v[156:157], v[152:153], v[210:211]
	v_pk_fma_f32 v[148:149], v[148:149], v[144:145], v[212:213]
	v_pk_fma_f32 v[156:157], v[156:157], v[152:153], v[212:213]
	v_pk_mul_f32 v[148:149], v[148:149], v[144:145]
	v_pk_mul_f32 v[156:157], v[156:157], v[152:153]
	v_max_f32_e32 v150, 0, v76
	v_max_f32_e32 v151, 0, v77
	v_max_f32_e32 v166, 0, v78
	v_max_f32_e32 v167, 0, v79
	v_pk_mul_f32 v[148:149], v[148:149], v[146:147]
	v_pk_mul_f32 v[156:157], v[156:157], v[154:155]
	v_fma_f32 v76, -|v76|, v148, v150
	v_fma_f32 v77, -|v77|, v149, v151
	v_fma_f32 v78, -|v78|, v156, v166
	v_fma_f32 v79, -|v79|, v157, v167
	v_pk_mul_f32 v[226:227], v[76:77], v[76:77]
	v_pk_fma_f32 v[226:227], v[78:79], v[78:79], v[226:227]
	v_cvt_pk_bf16_f32 v168, v76, v77
	v_cvt_pk_bf16_f32 v169, v78, v79
	v_fma_f32 v144, |v72|, v196, 1.0
	v_fma_f32 v145, |v73|, v196, 1.0
	v_fma_f32 v152, |v74|, v196, 1.0
	v_fma_f32 v153, |v75|, v196, 1.0
	v_pk_mul_f32 v[146:147], v[72:73], v[72:73]
	v_pk_mul_f32 v[154:155], v[74:75], v[74:75]
	v_rcp_f32_e32 v144, v144
	v_rcp_f32_e32 v145, v145
	v_rcp_f32_e32 v152, v152
	v_rcp_f32_e32 v153, v153
	v_pk_mul_f32 v[146:147], v[146:147], v[214:215]
	v_pk_mul_f32 v[154:155], v[154:155], v[214:215]
	v_exp_f32_e32 v146, v146
	v_exp_f32_e32 v147, v147
	v_exp_f32_e32 v154, v154
	v_exp_f32_e32 v155, v155
	v_pk_fma_f32 v[148:149], v[144:145], v[198:199], v[200:201]
	v_pk_fma_f32 v[156:157], v[152:153], v[198:199], v[200:201]
	v_pk_fma_f32 v[148:149], v[148:149], v[144:145], v[202:203]
	v_pk_fma_f32 v[156:157], v[156:157], v[152:153], v[202:203]
	v_pk_fma_f32 v[148:149], v[148:149], v[144:145], v[210:211]
	v_pk_fma_f32 v[156:157], v[156:157], v[152:153], v[210:211]
	v_pk_fma_f32 v[148:149], v[148:149], v[144:145], v[212:213]
	v_pk_fma_f32 v[156:157], v[156:157], v[152:153], v[212:213]
	v_pk_mul_f32 v[148:149], v[148:149], v[144:145]
	v_pk_mul_f32 v[156:157], v[156:157], v[152:153]
	v_max_f32_e32 v150, 0, v72
	v_max_f32_e32 v151, 0, v73
	v_max_f32_e32 v166, 0, v74
	v_max_f32_e32 v167, 0, v75
	v_pk_mul_f32 v[148:149], v[148:149], v[146:147]
	v_pk_mul_f32 v[156:157], v[156:157], v[154:155]
	v_fma_f32 v72, -|v72|, v148, v150
	v_fma_f32 v73, -|v73|, v149, v151
	v_fma_f32 v74, -|v74|, v156, v166
	v_fma_f32 v75, -|v75|, v157, v167
	v_pk_fma_f32 v[226:227], v[72:73], v[72:73], v[226:227]
	v_pk_fma_f32 v[226:227], v[74:75], v[74:75], v[226:227]
	v_cvt_pk_bf16_f32 v170, v72, v73
	v_cvt_pk_bf16_f32 v171, v74, v75
	s_mul_i32 s2, s33, 0x60
	buffer_store_dwordx4 v[168:171], v216, s[72:75], s2 offen
	v_fma_f32 v144, |v68|, v196, 1.0
	v_fma_f32 v145, |v69|, v196, 1.0
	v_fma_f32 v152, |v70|, v196, 1.0
	v_fma_f32 v153, |v71|, v196, 1.0
	v_pk_mul_f32 v[146:147], v[68:69], v[68:69]
	v_pk_mul_f32 v[154:155], v[70:71], v[70:71]
	v_rcp_f32_e32 v144, v144
	v_rcp_f32_e32 v145, v145
	v_rcp_f32_e32 v152, v152
	v_rcp_f32_e32 v153, v153
	v_pk_mul_f32 v[146:147], v[146:147], v[214:215]
	v_pk_mul_f32 v[154:155], v[154:155], v[214:215]
	v_exp_f32_e32 v146, v146
	v_exp_f32_e32 v147, v147
	v_exp_f32_e32 v154, v154
	v_exp_f32_e32 v155, v155
	v_pk_fma_f32 v[148:149], v[144:145], v[198:199], v[200:201]
	v_pk_fma_f32 v[156:157], v[152:153], v[198:199], v[200:201]
	v_pk_fma_f32 v[148:149], v[148:149], v[144:145], v[202:203]
	v_pk_fma_f32 v[156:157], v[156:157], v[152:153], v[202:203]
	v_pk_fma_f32 v[148:149], v[148:149], v[144:145], v[210:211]
	v_pk_fma_f32 v[156:157], v[156:157], v[152:153], v[210:211]
	v_pk_fma_f32 v[148:149], v[148:149], v[144:145], v[212:213]
	v_pk_fma_f32 v[156:157], v[156:157], v[152:153], v[212:213]
	v_pk_mul_f32 v[148:149], v[148:149], v[144:145]
	v_pk_mul_f32 v[156:157], v[156:157], v[152:153]
	v_max_f32_e32 v150, 0, v68
	v_max_f32_e32 v151, 0, v69
	v_max_f32_e32 v166, 0, v70
	v_max_f32_e32 v167, 0, v71
	v_pk_mul_f32 v[148:149], v[148:149], v[146:147]
	v_pk_mul_f32 v[156:157], v[156:157], v[154:155]
	v_fma_f32 v68, -|v68|, v148, v150
	v_fma_f32 v69, -|v69|, v149, v151
	v_fma_f32 v70, -|v70|, v156, v166
	v_fma_f32 v71, -|v71|, v157, v167
	v_pk_fma_f32 v[226:227], v[68:69], v[68:69], v[226:227]
	v_pk_fma_f32 v[226:227], v[70:71], v[70:71], v[226:227]
	v_cvt_pk_bf16_f32 v232, v68, v69
	v_cvt_pk_bf16_f32 v233, v70, v71
	v_fma_f32 v144, |v64|, v196, 1.0
	v_fma_f32 v145, |v65|, v196, 1.0
	v_fma_f32 v152, |v66|, v196, 1.0
	v_fma_f32 v153, |v67|, v196, 1.0
	v_pk_mul_f32 v[146:147], v[64:65], v[64:65]
	v_pk_mul_f32 v[154:155], v[66:67], v[66:67]
	v_rcp_f32_e32 v144, v144
	v_rcp_f32_e32 v145, v145
	v_rcp_f32_e32 v152, v152
	v_rcp_f32_e32 v153, v153
	v_pk_mul_f32 v[146:147], v[146:147], v[214:215]
	v_pk_mul_f32 v[154:155], v[154:155], v[214:215]
	v_exp_f32_e32 v146, v146
	v_exp_f32_e32 v147, v147
	v_exp_f32_e32 v154, v154
	v_exp_f32_e32 v155, v155
	v_pk_fma_f32 v[148:149], v[144:145], v[198:199], v[200:201]
	v_pk_fma_f32 v[156:157], v[152:153], v[198:199], v[200:201]
	v_pk_fma_f32 v[148:149], v[148:149], v[144:145], v[202:203]
	v_pk_fma_f32 v[156:157], v[156:157], v[152:153], v[202:203]
	v_pk_fma_f32 v[148:149], v[148:149], v[144:145], v[210:211]
	v_pk_fma_f32 v[156:157], v[156:157], v[152:153], v[210:211]
	v_pk_fma_f32 v[148:149], v[148:149], v[144:145], v[212:213]
	v_pk_fma_f32 v[156:157], v[156:157], v[152:153], v[212:213]
	v_pk_mul_f32 v[148:149], v[148:149], v[144:145]
	v_pk_mul_f32 v[156:157], v[156:157], v[152:153]
	v_max_f32_e32 v150, 0, v64
	v_max_f32_e32 v151, 0, v65
	v_max_f32_e32 v166, 0, v66
	v_max_f32_e32 v167, 0, v67
	v_pk_mul_f32 v[148:149], v[148:149], v[146:147]
	v_pk_mul_f32 v[156:157], v[156:157], v[154:155]
	v_fma_f32 v64, -|v64|, v148, v150
	v_fma_f32 v65, -|v65|, v149, v151
	v_fma_f32 v66, -|v66|, v156, v166
	v_fma_f32 v67, -|v67|, v157, v167
	v_pk_fma_f32 v[226:227], v[64:65], v[64:65], v[226:227]
	v_pk_fma_f32 v[226:227], v[66:67], v[66:67], v[226:227]
	v_cvt_pk_bf16_f32 v234, v64, v65
	v_cvt_pk_bf16_f32 v235, v66, v67
	buffer_store_dwordx4 v[232:235], v216, s[72:75], s2 offen offset:256
	v_add_f32_e32 v221, v226, v227
	v_fma_f32 v144, |v60|, v196, 1.0
	v_fma_f32 v145, |v61|, v196, 1.0
	v_fma_f32 v152, |v62|, v196, 1.0
	v_fma_f32 v153, |v63|, v196, 1.0
	v_pk_mul_f32 v[146:147], v[60:61], v[60:61]
	v_pk_mul_f32 v[154:155], v[62:63], v[62:63]
	v_rcp_f32_e32 v144, v144
	v_rcp_f32_e32 v145, v145
	v_rcp_f32_e32 v152, v152
	v_rcp_f32_e32 v153, v153
	v_pk_mul_f32 v[146:147], v[146:147], v[214:215]
	v_pk_mul_f32 v[154:155], v[154:155], v[214:215]
	v_exp_f32_e32 v146, v146
	v_exp_f32_e32 v147, v147
	v_exp_f32_e32 v154, v154
	v_exp_f32_e32 v155, v155
	v_pk_fma_f32 v[148:149], v[144:145], v[198:199], v[200:201]
	v_pk_fma_f32 v[156:157], v[152:153], v[198:199], v[200:201]
	v_pk_fma_f32 v[148:149], v[148:149], v[144:145], v[202:203]
	v_pk_fma_f32 v[156:157], v[156:157], v[152:153], v[202:203]
	v_pk_fma_f32 v[148:149], v[148:149], v[144:145], v[210:211]
	v_pk_fma_f32 v[156:157], v[156:157], v[152:153], v[210:211]
	v_pk_fma_f32 v[148:149], v[148:149], v[144:145], v[212:213]
	v_pk_fma_f32 v[156:157], v[156:157], v[152:153], v[212:213]
	v_pk_mul_f32 v[148:149], v[148:149], v[144:145]
	v_pk_mul_f32 v[156:157], v[156:157], v[152:153]
	v_max_f32_e32 v150, 0, v60
	v_max_f32_e32 v151, 0, v61
	v_max_f32_e32 v166, 0, v62
	v_max_f32_e32 v167, 0, v63
	v_pk_mul_f32 v[148:149], v[148:149], v[146:147]
	v_pk_mul_f32 v[156:157], v[156:157], v[154:155]
	v_fma_f32 v60, -|v60|, v148, v150
	v_fma_f32 v61, -|v61|, v149, v151
	v_fma_f32 v62, -|v62|, v156, v166
	v_fma_f32 v63, -|v63|, v157, v167
	v_pk_mul_f32 v[226:227], v[60:61], v[60:61]
	v_pk_fma_f32 v[226:227], v[62:63], v[62:63], v[226:227]
	v_cvt_pk_bf16_f32 v168, v60, v61
	v_cvt_pk_bf16_f32 v169, v62, v63
	v_fma_f32 v144, |v56|, v196, 1.0
	v_fma_f32 v145, |v57|, v196, 1.0
	v_fma_f32 v152, |v58|, v196, 1.0
	v_fma_f32 v153, |v59|, v196, 1.0
	v_pk_mul_f32 v[146:147], v[56:57], v[56:57]
	v_pk_mul_f32 v[154:155], v[58:59], v[58:59]
	v_rcp_f32_e32 v144, v144
	v_rcp_f32_e32 v145, v145
	v_rcp_f32_e32 v152, v152
	v_rcp_f32_e32 v153, v153
	v_pk_mul_f32 v[146:147], v[146:147], v[214:215]
	v_pk_mul_f32 v[154:155], v[154:155], v[214:215]
	v_exp_f32_e32 v146, v146
	v_exp_f32_e32 v147, v147
	v_exp_f32_e32 v154, v154
	v_exp_f32_e32 v155, v155
	v_pk_fma_f32 v[148:149], v[144:145], v[198:199], v[200:201]
	v_pk_fma_f32 v[156:157], v[152:153], v[198:199], v[200:201]
	v_pk_fma_f32 v[148:149], v[148:149], v[144:145], v[202:203]
	v_pk_fma_f32 v[156:157], v[156:157], v[152:153], v[202:203]
	v_pk_fma_f32 v[148:149], v[148:149], v[144:145], v[210:211]
	v_pk_fma_f32 v[156:157], v[156:157], v[152:153], v[210:211]
	v_pk_fma_f32 v[148:149], v[148:149], v[144:145], v[212:213]
	v_pk_fma_f32 v[156:157], v[156:157], v[152:153], v[212:213]
	v_pk_mul_f32 v[148:149], v[148:149], v[144:145]
	v_pk_mul_f32 v[156:157], v[156:157], v[152:153]
	v_max_f32_e32 v150, 0, v56
	v_max_f32_e32 v151, 0, v57
	v_max_f32_e32 v166, 0, v58
	v_max_f32_e32 v167, 0, v59
	v_pk_mul_f32 v[148:149], v[148:149], v[146:147]
	v_pk_mul_f32 v[156:157], v[156:157], v[154:155]
	v_fma_f32 v56, -|v56|, v148, v150
	v_fma_f32 v57, -|v57|, v149, v151
	v_fma_f32 v58, -|v58|, v156, v166
	v_fma_f32 v59, -|v59|, v157, v167
	v_pk_fma_f32 v[226:227], v[56:57], v[56:57], v[226:227]
	v_pk_fma_f32 v[226:227], v[58:59], v[58:59], v[226:227]
	v_cvt_pk_bf16_f32 v170, v56, v57
	v_cvt_pk_bf16_f32 v171, v58, v59
	s_mul_i32 s2, s33, 0x100
	buffer_store_dwordx4 v[168:171], v216, s[72:75], s2 offen
	v_fma_f32 v144, |v52|, v196, 1.0
	v_fma_f32 v145, |v53|, v196, 1.0
	v_fma_f32 v152, |v54|, v196, 1.0
	v_fma_f32 v153, |v55|, v196, 1.0
	v_pk_mul_f32 v[146:147], v[52:53], v[52:53]
	v_pk_mul_f32 v[154:155], v[54:55], v[54:55]
	v_rcp_f32_e32 v144, v144
	v_rcp_f32_e32 v145, v145
	v_rcp_f32_e32 v152, v152
	v_rcp_f32_e32 v153, v153
	v_pk_mul_f32 v[146:147], v[146:147], v[214:215]
	v_pk_mul_f32 v[154:155], v[154:155], v[214:215]
	v_exp_f32_e32 v146, v146
	v_exp_f32_e32 v147, v147
	v_exp_f32_e32 v154, v154
	v_exp_f32_e32 v155, v155
	v_pk_fma_f32 v[148:149], v[144:145], v[198:199], v[200:201]
	v_pk_fma_f32 v[156:157], v[152:153], v[198:199], v[200:201]
	v_pk_fma_f32 v[148:149], v[148:149], v[144:145], v[202:203]
	v_pk_fma_f32 v[156:157], v[156:157], v[152:153], v[202:203]
	v_pk_fma_f32 v[148:149], v[148:149], v[144:145], v[210:211]
	v_pk_fma_f32 v[156:157], v[156:157], v[152:153], v[210:211]
	v_pk_fma_f32 v[148:149], v[148:149], v[144:145], v[212:213]
	v_pk_fma_f32 v[156:157], v[156:157], v[152:153], v[212:213]
	v_pk_mul_f32 v[148:149], v[148:149], v[144:145]
	v_pk_mul_f32 v[156:157], v[156:157], v[152:153]
	v_max_f32_e32 v150, 0, v52
	v_max_f32_e32 v151, 0, v53
	v_max_f32_e32 v166, 0, v54
	v_max_f32_e32 v167, 0, v55
	v_pk_mul_f32 v[148:149], v[148:149], v[146:147]
	v_pk_mul_f32 v[156:157], v[156:157], v[154:155]
	v_fma_f32 v52, -|v52|, v148, v150
	v_fma_f32 v53, -|v53|, v149, v151
	v_fma_f32 v54, -|v54|, v156, v166
	v_fma_f32 v55, -|v55|, v157, v167
	v_pk_fma_f32 v[226:227], v[52:53], v[52:53], v[226:227]
	v_pk_fma_f32 v[226:227], v[54:55], v[54:55], v[226:227]
	v_cvt_pk_bf16_f32 v232, v52, v53
	v_cvt_pk_bf16_f32 v233, v54, v55
	v_fma_f32 v144, |v48|, v196, 1.0
	v_fma_f32 v145, |v49|, v196, 1.0
	v_fma_f32 v152, |v50|, v196, 1.0
	v_fma_f32 v153, |v51|, v196, 1.0
	v_pk_mul_f32 v[146:147], v[48:49], v[48:49]
	v_pk_mul_f32 v[154:155], v[50:51], v[50:51]
	v_rcp_f32_e32 v144, v144
	v_rcp_f32_e32 v145, v145
	v_rcp_f32_e32 v152, v152
	v_rcp_f32_e32 v153, v153
	v_pk_mul_f32 v[146:147], v[146:147], v[214:215]
	v_pk_mul_f32 v[154:155], v[154:155], v[214:215]
	v_exp_f32_e32 v146, v146
	v_exp_f32_e32 v147, v147
	v_exp_f32_e32 v154, v154
	v_exp_f32_e32 v155, v155
	v_pk_fma_f32 v[148:149], v[144:145], v[198:199], v[200:201]
	v_pk_fma_f32 v[156:157], v[152:153], v[198:199], v[200:201]
	v_pk_fma_f32 v[148:149], v[148:149], v[144:145], v[202:203]
	v_pk_fma_f32 v[156:157], v[156:157], v[152:153], v[202:203]
	v_pk_fma_f32 v[148:149], v[148:149], v[144:145], v[210:211]
	v_pk_fma_f32 v[156:157], v[156:157], v[152:153], v[210:211]
	v_pk_fma_f32 v[148:149], v[148:149], v[144:145], v[212:213]
	v_pk_fma_f32 v[156:157], v[156:157], v[152:153], v[212:213]
	v_pk_mul_f32 v[148:149], v[148:149], v[144:145]
	v_pk_mul_f32 v[156:157], v[156:157], v[152:153]
	v_max_f32_e32 v150, 0, v48
	v_max_f32_e32 v151, 0, v49
	v_max_f32_e32 v166, 0, v50
	v_max_f32_e32 v167, 0, v51
	v_pk_mul_f32 v[148:149], v[148:149], v[146:147]
	v_pk_mul_f32 v[156:157], v[156:157], v[154:155]
	v_fma_f32 v48, -|v48|, v148, v150
	v_fma_f32 v49, -|v49|, v149, v151
	v_fma_f32 v50, -|v50|, v156, v166
	v_fma_f32 v51, -|v51|, v157, v167
	v_pk_fma_f32 v[226:227], v[48:49], v[48:49], v[226:227]
	v_pk_fma_f32 v[226:227], v[50:51], v[50:51], v[226:227]
	v_cvt_pk_bf16_f32 v234, v48, v49
	v_cvt_pk_bf16_f32 v235, v50, v51
	buffer_store_dwordx4 v[232:235], v216, s[72:75], s2 offen offset:256
	v_add_f32_e32 v222, v226, v227
	v_fma_f32 v144, |v44|, v196, 1.0
	v_fma_f32 v145, |v45|, v196, 1.0
	v_fma_f32 v152, |v46|, v196, 1.0
	v_fma_f32 v153, |v47|, v196, 1.0
	v_pk_mul_f32 v[146:147], v[44:45], v[44:45]
	v_pk_mul_f32 v[154:155], v[46:47], v[46:47]
	v_rcp_f32_e32 v144, v144
	v_rcp_f32_e32 v145, v145
	v_rcp_f32_e32 v152, v152
	v_rcp_f32_e32 v153, v153
	v_pk_mul_f32 v[146:147], v[146:147], v[214:215]
	v_pk_mul_f32 v[154:155], v[154:155], v[214:215]
	v_exp_f32_e32 v146, v146
	v_exp_f32_e32 v147, v147
	v_exp_f32_e32 v154, v154
	v_exp_f32_e32 v155, v155
	v_pk_fma_f32 v[148:149], v[144:145], v[198:199], v[200:201]
	v_pk_fma_f32 v[156:157], v[152:153], v[198:199], v[200:201]
	v_pk_fma_f32 v[148:149], v[148:149], v[144:145], v[202:203]
	v_pk_fma_f32 v[156:157], v[156:157], v[152:153], v[202:203]
	v_pk_fma_f32 v[148:149], v[148:149], v[144:145], v[210:211]
	v_pk_fma_f32 v[156:157], v[156:157], v[152:153], v[210:211]
	v_pk_fma_f32 v[148:149], v[148:149], v[144:145], v[212:213]
	v_pk_fma_f32 v[156:157], v[156:157], v[152:153], v[212:213]
	v_pk_mul_f32 v[148:149], v[148:149], v[144:145]
	v_pk_mul_f32 v[156:157], v[156:157], v[152:153]
	v_max_f32_e32 v150, 0, v44
	v_max_f32_e32 v151, 0, v45
	v_max_f32_e32 v166, 0, v46
	v_max_f32_e32 v167, 0, v47
	v_pk_mul_f32 v[148:149], v[148:149], v[146:147]
	v_pk_mul_f32 v[156:157], v[156:157], v[154:155]
	v_fma_f32 v44, -|v44|, v148, v150
	v_fma_f32 v45, -|v45|, v149, v151
	v_fma_f32 v46, -|v46|, v156, v166
	v_fma_f32 v47, -|v47|, v157, v167
	v_pk_mul_f32 v[226:227], v[44:45], v[44:45]
	v_pk_fma_f32 v[226:227], v[46:47], v[46:47], v[226:227]
	v_cvt_pk_bf16_f32 v168, v44, v45
	v_cvt_pk_bf16_f32 v169, v46, v47
	v_fma_f32 v144, |v40|, v196, 1.0
	v_fma_f32 v145, |v41|, v196, 1.0
	v_fma_f32 v152, |v42|, v196, 1.0
	v_fma_f32 v153, |v43|, v196, 1.0
	v_pk_mul_f32 v[146:147], v[40:41], v[40:41]
	v_pk_mul_f32 v[154:155], v[42:43], v[42:43]
	v_rcp_f32_e32 v144, v144
	v_rcp_f32_e32 v145, v145
	v_rcp_f32_e32 v152, v152
	v_rcp_f32_e32 v153, v153
	v_pk_mul_f32 v[146:147], v[146:147], v[214:215]
	v_pk_mul_f32 v[154:155], v[154:155], v[214:215]
	v_exp_f32_e32 v146, v146
	v_exp_f32_e32 v147, v147
	v_exp_f32_e32 v154, v154
	v_exp_f32_e32 v155, v155
	v_pk_fma_f32 v[148:149], v[144:145], v[198:199], v[200:201]
	v_pk_fma_f32 v[156:157], v[152:153], v[198:199], v[200:201]
	v_pk_fma_f32 v[148:149], v[148:149], v[144:145], v[202:203]
	v_pk_fma_f32 v[156:157], v[156:157], v[152:153], v[202:203]
	v_pk_fma_f32 v[148:149], v[148:149], v[144:145], v[210:211]
	v_pk_fma_f32 v[156:157], v[156:157], v[152:153], v[210:211]
	v_pk_fma_f32 v[148:149], v[148:149], v[144:145], v[212:213]
	v_pk_fma_f32 v[156:157], v[156:157], v[152:153], v[212:213]
	v_pk_mul_f32 v[148:149], v[148:149], v[144:145]
	v_pk_mul_f32 v[156:157], v[156:157], v[152:153]
	v_max_f32_e32 v150, 0, v40
	v_max_f32_e32 v151, 0, v41
	v_max_f32_e32 v166, 0, v42
	v_max_f32_e32 v167, 0, v43
	v_pk_mul_f32 v[148:149], v[148:149], v[146:147]
	v_pk_mul_f32 v[156:157], v[156:157], v[154:155]
	v_fma_f32 v40, -|v40|, v148, v150
	v_fma_f32 v41, -|v41|, v149, v151
	v_fma_f32 v42, -|v42|, v156, v166
	v_fma_f32 v43, -|v43|, v157, v167
	v_pk_fma_f32 v[226:227], v[40:41], v[40:41], v[226:227]
	v_pk_fma_f32 v[226:227], v[42:43], v[42:43], v[226:227]
	v_cvt_pk_bf16_f32 v170, v40, v41
	v_cvt_pk_bf16_f32 v171, v42, v43
	s_mul_i32 s2, s33, 0x120
	buffer_store_dwordx4 v[168:171], v216, s[72:75], s2 offen
	v_fma_f32 v144, |v36|, v196, 1.0
	v_fma_f32 v145, |v37|, v196, 1.0
	v_fma_f32 v152, |v38|, v196, 1.0
	v_fma_f32 v153, |v39|, v196, 1.0
	v_pk_mul_f32 v[146:147], v[36:37], v[36:37]
	v_pk_mul_f32 v[154:155], v[38:39], v[38:39]
	v_rcp_f32_e32 v144, v144
	v_rcp_f32_e32 v145, v145
	v_rcp_f32_e32 v152, v152
	v_rcp_f32_e32 v153, v153
	v_pk_mul_f32 v[146:147], v[146:147], v[214:215]
	v_pk_mul_f32 v[154:155], v[154:155], v[214:215]
	v_exp_f32_e32 v146, v146
	v_exp_f32_e32 v147, v147
	v_exp_f32_e32 v154, v154
	v_exp_f32_e32 v155, v155
	v_pk_fma_f32 v[148:149], v[144:145], v[198:199], v[200:201]
	v_pk_fma_f32 v[156:157], v[152:153], v[198:199], v[200:201]
	v_pk_fma_f32 v[148:149], v[148:149], v[144:145], v[202:203]
	v_pk_fma_f32 v[156:157], v[156:157], v[152:153], v[202:203]
	v_pk_fma_f32 v[148:149], v[148:149], v[144:145], v[210:211]
	v_pk_fma_f32 v[156:157], v[156:157], v[152:153], v[210:211]
	v_pk_fma_f32 v[148:149], v[148:149], v[144:145], v[212:213]
	v_pk_fma_f32 v[156:157], v[156:157], v[152:153], v[212:213]
	v_pk_mul_f32 v[148:149], v[148:149], v[144:145]
	v_pk_mul_f32 v[156:157], v[156:157], v[152:153]
	v_max_f32_e32 v150, 0, v36
	v_max_f32_e32 v151, 0, v37
	v_max_f32_e32 v166, 0, v38
	v_max_f32_e32 v167, 0, v39
	v_pk_mul_f32 v[148:149], v[148:149], v[146:147]
	v_pk_mul_f32 v[156:157], v[156:157], v[154:155]
	v_fma_f32 v36, -|v36|, v148, v150
	v_fma_f32 v37, -|v37|, v149, v151
	v_fma_f32 v38, -|v38|, v156, v166
	v_fma_f32 v39, -|v39|, v157, v167
	v_pk_fma_f32 v[226:227], v[36:37], v[36:37], v[226:227]
	v_pk_fma_f32 v[226:227], v[38:39], v[38:39], v[226:227]
	v_cvt_pk_bf16_f32 v232, v36, v37
	v_cvt_pk_bf16_f32 v233, v38, v39
	v_fma_f32 v144, |v32|, v196, 1.0
	v_fma_f32 v145, |v33|, v196, 1.0
	v_fma_f32 v152, |v34|, v196, 1.0
	v_fma_f32 v153, |v35|, v196, 1.0
	v_pk_mul_f32 v[146:147], v[32:33], v[32:33]
	v_pk_mul_f32 v[154:155], v[34:35], v[34:35]
	v_rcp_f32_e32 v144, v144
	v_rcp_f32_e32 v145, v145
	v_rcp_f32_e32 v152, v152
	v_rcp_f32_e32 v153, v153
	v_pk_mul_f32 v[146:147], v[146:147], v[214:215]
	v_pk_mul_f32 v[154:155], v[154:155], v[214:215]
	v_exp_f32_e32 v146, v146
	v_exp_f32_e32 v147, v147
	v_exp_f32_e32 v154, v154
	v_exp_f32_e32 v155, v155
	v_pk_fma_f32 v[148:149], v[144:145], v[198:199], v[200:201]
	v_pk_fma_f32 v[156:157], v[152:153], v[198:199], v[200:201]
	v_pk_fma_f32 v[148:149], v[148:149], v[144:145], v[202:203]
	v_pk_fma_f32 v[156:157], v[156:157], v[152:153], v[202:203]
	v_pk_fma_f32 v[148:149], v[148:149], v[144:145], v[210:211]
	v_pk_fma_f32 v[156:157], v[156:157], v[152:153], v[210:211]
	v_pk_fma_f32 v[148:149], v[148:149], v[144:145], v[212:213]
	v_pk_fma_f32 v[156:157], v[156:157], v[152:153], v[212:213]
	v_pk_mul_f32 v[148:149], v[148:149], v[144:145]
	v_pk_mul_f32 v[156:157], v[156:157], v[152:153]
	v_max_f32_e32 v150, 0, v32
	v_max_f32_e32 v151, 0, v33
	v_max_f32_e32 v166, 0, v34
	v_max_f32_e32 v167, 0, v35
	v_pk_mul_f32 v[148:149], v[148:149], v[146:147]
	v_pk_mul_f32 v[156:157], v[156:157], v[154:155]
	v_fma_f32 v32, -|v32|, v148, v150
	v_fma_f32 v33, -|v33|, v149, v151
	v_fma_f32 v34, -|v34|, v156, v166
	v_fma_f32 v35, -|v35|, v157, v167
	v_pk_fma_f32 v[226:227], v[32:33], v[32:33], v[226:227]
	v_pk_fma_f32 v[226:227], v[34:35], v[34:35], v[226:227]
	v_cvt_pk_bf16_f32 v234, v32, v33
	v_cvt_pk_bf16_f32 v235, v34, v35
	buffer_store_dwordx4 v[232:235], v216, s[72:75], s2 offen offset:256
	v_add_f32_e32 v223, v226, v227
	v_fma_f32 v144, |v28|, v196, 1.0
	v_fma_f32 v145, |v29|, v196, 1.0
	v_fma_f32 v152, |v30|, v196, 1.0
	v_fma_f32 v153, |v31|, v196, 1.0
	v_pk_mul_f32 v[146:147], v[28:29], v[28:29]
	v_pk_mul_f32 v[154:155], v[30:31], v[30:31]
	v_rcp_f32_e32 v144, v144
	v_rcp_f32_e32 v145, v145
	v_rcp_f32_e32 v152, v152
	v_rcp_f32_e32 v153, v153
	v_pk_mul_f32 v[146:147], v[146:147], v[214:215]
	v_pk_mul_f32 v[154:155], v[154:155], v[214:215]
	v_exp_f32_e32 v146, v146
	v_exp_f32_e32 v147, v147
	v_exp_f32_e32 v154, v154
	v_exp_f32_e32 v155, v155
	v_pk_fma_f32 v[148:149], v[144:145], v[198:199], v[200:201]
	v_pk_fma_f32 v[156:157], v[152:153], v[198:199], v[200:201]
	v_pk_fma_f32 v[148:149], v[148:149], v[144:145], v[202:203]
	v_pk_fma_f32 v[156:157], v[156:157], v[152:153], v[202:203]
	v_pk_fma_f32 v[148:149], v[148:149], v[144:145], v[210:211]
	v_pk_fma_f32 v[156:157], v[156:157], v[152:153], v[210:211]
	v_pk_fma_f32 v[148:149], v[148:149], v[144:145], v[212:213]
	v_pk_fma_f32 v[156:157], v[156:157], v[152:153], v[212:213]
	v_pk_mul_f32 v[148:149], v[148:149], v[144:145]
	v_pk_mul_f32 v[156:157], v[156:157], v[152:153]
	v_max_f32_e32 v150, 0, v28
	v_max_f32_e32 v151, 0, v29
	v_max_f32_e32 v166, 0, v30
	v_max_f32_e32 v167, 0, v31
	v_pk_mul_f32 v[148:149], v[148:149], v[146:147]
	v_pk_mul_f32 v[156:157], v[156:157], v[154:155]
	v_fma_f32 v28, -|v28|, v148, v150
	v_fma_f32 v29, -|v29|, v149, v151
	v_fma_f32 v30, -|v30|, v156, v166
	v_fma_f32 v31, -|v31|, v157, v167
	v_pk_mul_f32 v[226:227], v[28:29], v[28:29]
	v_pk_fma_f32 v[226:227], v[30:31], v[30:31], v[226:227]
	v_cvt_pk_bf16_f32 v168, v28, v29
	v_cvt_pk_bf16_f32 v169, v30, v31
	v_fma_f32 v144, |v24|, v196, 1.0
	v_fma_f32 v145, |v25|, v196, 1.0
	v_fma_f32 v152, |v26|, v196, 1.0
	v_fma_f32 v153, |v27|, v196, 1.0
	v_pk_mul_f32 v[146:147], v[24:25], v[24:25]
	v_pk_mul_f32 v[154:155], v[26:27], v[26:27]
	v_rcp_f32_e32 v144, v144
	v_rcp_f32_e32 v145, v145
	v_rcp_f32_e32 v152, v152
	v_rcp_f32_e32 v153, v153
	v_pk_mul_f32 v[146:147], v[146:147], v[214:215]
	v_pk_mul_f32 v[154:155], v[154:155], v[214:215]
	v_exp_f32_e32 v146, v146
	v_exp_f32_e32 v147, v147
	v_exp_f32_e32 v154, v154
	v_exp_f32_e32 v155, v155
	v_pk_fma_f32 v[148:149], v[144:145], v[198:199], v[200:201]
	v_pk_fma_f32 v[156:157], v[152:153], v[198:199], v[200:201]
	v_pk_fma_f32 v[148:149], v[148:149], v[144:145], v[202:203]
	v_pk_fma_f32 v[156:157], v[156:157], v[152:153], v[202:203]
	v_pk_fma_f32 v[148:149], v[148:149], v[144:145], v[210:211]
	v_pk_fma_f32 v[156:157], v[156:157], v[152:153], v[210:211]
	v_pk_fma_f32 v[148:149], v[148:149], v[144:145], v[212:213]
	v_pk_fma_f32 v[156:157], v[156:157], v[152:153], v[212:213]
	v_pk_mul_f32 v[148:149], v[148:149], v[144:145]
	v_pk_mul_f32 v[156:157], v[156:157], v[152:153]
	v_max_f32_e32 v150, 0, v24
	v_max_f32_e32 v151, 0, v25
	v_max_f32_e32 v166, 0, v26
	v_max_f32_e32 v167, 0, v27
	v_pk_mul_f32 v[148:149], v[148:149], v[146:147]
	v_pk_mul_f32 v[156:157], v[156:157], v[154:155]
	v_fma_f32 v24, -|v24|, v148, v150
	v_fma_f32 v25, -|v25|, v149, v151
	v_fma_f32 v26, -|v26|, v156, v166
	v_fma_f32 v27, -|v27|, v157, v167
	v_pk_fma_f32 v[226:227], v[24:25], v[24:25], v[226:227]
	v_pk_fma_f32 v[226:227], v[26:27], v[26:27], v[226:227]
	v_cvt_pk_bf16_f32 v170, v24, v25
	v_cvt_pk_bf16_f32 v171, v26, v27
	s_mul_i32 s2, s33, 0x140
	buffer_store_dwordx4 v[168:171], v216, s[72:75], s2 offen
	v_fma_f32 v144, |v20|, v196, 1.0
	v_fma_f32 v145, |v21|, v196, 1.0
	v_fma_f32 v152, |v22|, v196, 1.0
	v_fma_f32 v153, |v23|, v196, 1.0
	v_pk_mul_f32 v[146:147], v[20:21], v[20:21]
	v_pk_mul_f32 v[154:155], v[22:23], v[22:23]
	v_rcp_f32_e32 v144, v144
	v_rcp_f32_e32 v145, v145
	v_rcp_f32_e32 v152, v152
	v_rcp_f32_e32 v153, v153
	v_pk_mul_f32 v[146:147], v[146:147], v[214:215]
	v_pk_mul_f32 v[154:155], v[154:155], v[214:215]
	v_exp_f32_e32 v146, v146
	v_exp_f32_e32 v147, v147
	v_exp_f32_e32 v154, v154
	v_exp_f32_e32 v155, v155
	v_pk_fma_f32 v[148:149], v[144:145], v[198:199], v[200:201]
	v_pk_fma_f32 v[156:157], v[152:153], v[198:199], v[200:201]
	v_pk_fma_f32 v[148:149], v[148:149], v[144:145], v[202:203]
	v_pk_fma_f32 v[156:157], v[156:157], v[152:153], v[202:203]
	v_pk_fma_f32 v[148:149], v[148:149], v[144:145], v[210:211]
	v_pk_fma_f32 v[156:157], v[156:157], v[152:153], v[210:211]
	v_pk_fma_f32 v[148:149], v[148:149], v[144:145], v[212:213]
	v_pk_fma_f32 v[156:157], v[156:157], v[152:153], v[212:213]
	v_pk_mul_f32 v[148:149], v[148:149], v[144:145]
	v_pk_mul_f32 v[156:157], v[156:157], v[152:153]
	v_max_f32_e32 v150, 0, v20
	v_max_f32_e32 v151, 0, v21
	v_max_f32_e32 v166, 0, v22
	v_max_f32_e32 v167, 0, v23
	v_pk_mul_f32 v[148:149], v[148:149], v[146:147]
	v_pk_mul_f32 v[156:157], v[156:157], v[154:155]
	v_fma_f32 v20, -|v20|, v148, v150
	v_fma_f32 v21, -|v21|, v149, v151
	v_fma_f32 v22, -|v22|, v156, v166
	v_fma_f32 v23, -|v23|, v157, v167
	v_pk_fma_f32 v[226:227], v[20:21], v[20:21], v[226:227]
	v_pk_fma_f32 v[226:227], v[22:23], v[22:23], v[226:227]
	v_cvt_pk_bf16_f32 v232, v20, v21
	v_cvt_pk_bf16_f32 v233, v22, v23
	v_fma_f32 v144, |v16|, v196, 1.0
	v_fma_f32 v145, |v17|, v196, 1.0
	v_fma_f32 v152, |v18|, v196, 1.0
	v_fma_f32 v153, |v19|, v196, 1.0
	v_pk_mul_f32 v[146:147], v[16:17], v[16:17]
	v_pk_mul_f32 v[154:155], v[18:19], v[18:19]
	v_rcp_f32_e32 v144, v144
	v_rcp_f32_e32 v145, v145
	v_rcp_f32_e32 v152, v152
	v_rcp_f32_e32 v153, v153
	v_pk_mul_f32 v[146:147], v[146:147], v[214:215]
	v_pk_mul_f32 v[154:155], v[154:155], v[214:215]
	v_exp_f32_e32 v146, v146
	v_exp_f32_e32 v147, v147
	v_exp_f32_e32 v154, v154
	v_exp_f32_e32 v155, v155
	v_pk_fma_f32 v[148:149], v[144:145], v[198:199], v[200:201]
	v_pk_fma_f32 v[156:157], v[152:153], v[198:199], v[200:201]
	v_pk_fma_f32 v[148:149], v[148:149], v[144:145], v[202:203]
	v_pk_fma_f32 v[156:157], v[156:157], v[152:153], v[202:203]
	v_pk_fma_f32 v[148:149], v[148:149], v[144:145], v[210:211]
	v_pk_fma_f32 v[156:157], v[156:157], v[152:153], v[210:211]
	v_pk_fma_f32 v[148:149], v[148:149], v[144:145], v[212:213]
	v_pk_fma_f32 v[156:157], v[156:157], v[152:153], v[212:213]
	v_pk_mul_f32 v[148:149], v[148:149], v[144:145]
	v_pk_mul_f32 v[156:157], v[156:157], v[152:153]
	v_max_f32_e32 v150, 0, v16
	v_max_f32_e32 v151, 0, v17
	v_max_f32_e32 v166, 0, v18
	v_max_f32_e32 v167, 0, v19
	v_pk_mul_f32 v[148:149], v[148:149], v[146:147]
	v_pk_mul_f32 v[156:157], v[156:157], v[154:155]
	v_fma_f32 v16, -|v16|, v148, v150
	v_fma_f32 v17, -|v17|, v149, v151
	v_fma_f32 v18, -|v18|, v156, v166
	v_fma_f32 v19, -|v19|, v157, v167
	v_pk_fma_f32 v[226:227], v[16:17], v[16:17], v[226:227]
	v_pk_fma_f32 v[226:227], v[18:19], v[18:19], v[226:227]
	v_cvt_pk_bf16_f32 v234, v16, v17
	v_cvt_pk_bf16_f32 v235, v18, v19
	buffer_store_dwordx4 v[232:235], v216, s[72:75], s2 offen offset:256
	v_add_f32_e32 v224, v226, v227
	v_fma_f32 v144, |v12|, v196, 1.0
	v_fma_f32 v145, |v13|, v196, 1.0
	v_fma_f32 v152, |v14|, v196, 1.0
	v_fma_f32 v153, |v15|, v196, 1.0
	v_pk_mul_f32 v[146:147], v[12:13], v[12:13]
	v_pk_mul_f32 v[154:155], v[14:15], v[14:15]
	v_rcp_f32_e32 v144, v144
	v_rcp_f32_e32 v145, v145
	v_rcp_f32_e32 v152, v152
	v_rcp_f32_e32 v153, v153
	v_pk_mul_f32 v[146:147], v[146:147], v[214:215]
	v_pk_mul_f32 v[154:155], v[154:155], v[214:215]
	v_exp_f32_e32 v146, v146
	v_exp_f32_e32 v147, v147
	v_exp_f32_e32 v154, v154
	v_exp_f32_e32 v155, v155
	v_pk_fma_f32 v[148:149], v[144:145], v[198:199], v[200:201]
	v_pk_fma_f32 v[156:157], v[152:153], v[198:199], v[200:201]
	v_pk_fma_f32 v[148:149], v[148:149], v[144:145], v[202:203]
	v_pk_fma_f32 v[156:157], v[156:157], v[152:153], v[202:203]
	v_pk_fma_f32 v[148:149], v[148:149], v[144:145], v[210:211]
	v_pk_fma_f32 v[156:157], v[156:157], v[152:153], v[210:211]
	v_pk_fma_f32 v[148:149], v[148:149], v[144:145], v[212:213]
	v_pk_fma_f32 v[156:157], v[156:157], v[152:153], v[212:213]
	v_pk_mul_f32 v[148:149], v[148:149], v[144:145]
	v_pk_mul_f32 v[156:157], v[156:157], v[152:153]
	v_max_f32_e32 v150, 0, v12
	v_max_f32_e32 v151, 0, v13
	v_max_f32_e32 v166, 0, v14
	v_max_f32_e32 v167, 0, v15
	v_pk_mul_f32 v[148:149], v[148:149], v[146:147]
	v_pk_mul_f32 v[156:157], v[156:157], v[154:155]
	v_fma_f32 v12, -|v12|, v148, v150
	v_fma_f32 v13, -|v13|, v149, v151
	v_fma_f32 v14, -|v14|, v156, v166
	v_fma_f32 v15, -|v15|, v157, v167
	v_pk_mul_f32 v[226:227], v[12:13], v[12:13]
	v_pk_fma_f32 v[226:227], v[14:15], v[14:15], v[226:227]
	v_cvt_pk_bf16_f32 v168, v12, v13
	v_cvt_pk_bf16_f32 v169, v14, v15
	v_fma_f32 v144, |v8|, v196, 1.0
	v_fma_f32 v145, |v9|, v196, 1.0
	v_fma_f32 v152, |v10|, v196, 1.0
	v_fma_f32 v153, |v11|, v196, 1.0
	v_pk_mul_f32 v[146:147], v[8:9], v[8:9]
	v_pk_mul_f32 v[154:155], v[10:11], v[10:11]
	v_rcp_f32_e32 v144, v144
	v_rcp_f32_e32 v145, v145
	v_rcp_f32_e32 v152, v152
	v_rcp_f32_e32 v153, v153
	v_pk_mul_f32 v[146:147], v[146:147], v[214:215]
	v_pk_mul_f32 v[154:155], v[154:155], v[214:215]
	v_exp_f32_e32 v146, v146
	v_exp_f32_e32 v147, v147
	v_exp_f32_e32 v154, v154
	v_exp_f32_e32 v155, v155
	v_pk_fma_f32 v[148:149], v[144:145], v[198:199], v[200:201]
	v_pk_fma_f32 v[156:157], v[152:153], v[198:199], v[200:201]
	v_pk_fma_f32 v[148:149], v[148:149], v[144:145], v[202:203]
	v_pk_fma_f32 v[156:157], v[156:157], v[152:153], v[202:203]
	v_pk_fma_f32 v[148:149], v[148:149], v[144:145], v[210:211]
	v_pk_fma_f32 v[156:157], v[156:157], v[152:153], v[210:211]
	v_pk_fma_f32 v[148:149], v[148:149], v[144:145], v[212:213]
	v_pk_fma_f32 v[156:157], v[156:157], v[152:153], v[212:213]
	v_pk_mul_f32 v[148:149], v[148:149], v[144:145]
	v_pk_mul_f32 v[156:157], v[156:157], v[152:153]
	v_max_f32_e32 v150, 0, v8
	v_max_f32_e32 v151, 0, v9
	v_max_f32_e32 v166, 0, v10
	v_max_f32_e32 v167, 0, v11
	v_pk_mul_f32 v[148:149], v[148:149], v[146:147]
	v_pk_mul_f32 v[156:157], v[156:157], v[154:155]
	v_fma_f32 v8, -|v8|, v148, v150
	v_fma_f32 v9, -|v9|, v149, v151
	v_fma_f32 v10, -|v10|, v156, v166
	v_fma_f32 v11, -|v11|, v157, v167
	v_pk_fma_f32 v[226:227], v[8:9], v[8:9], v[226:227]
	v_pk_fma_f32 v[226:227], v[10:11], v[10:11], v[226:227]
	v_cvt_pk_bf16_f32 v170, v8, v9
	v_cvt_pk_bf16_f32 v171, v10, v11
	s_mul_i32 s2, s33, 0x160
	buffer_store_dwordx4 v[168:171], v216, s[72:75], s2 offen
	v_fma_f32 v144, |v4|, v196, 1.0
	v_fma_f32 v145, |v5|, v196, 1.0
	v_fma_f32 v152, |v6|, v196, 1.0
	v_fma_f32 v153, |v7|, v196, 1.0
	v_pk_mul_f32 v[146:147], v[4:5], v[4:5]
	v_pk_mul_f32 v[154:155], v[6:7], v[6:7]
	v_rcp_f32_e32 v144, v144
	v_rcp_f32_e32 v145, v145
	v_rcp_f32_e32 v152, v152
	v_rcp_f32_e32 v153, v153
	v_pk_mul_f32 v[146:147], v[146:147], v[214:215]
	v_pk_mul_f32 v[154:155], v[154:155], v[214:215]
	v_exp_f32_e32 v146, v146
	v_exp_f32_e32 v147, v147
	v_exp_f32_e32 v154, v154
	v_exp_f32_e32 v155, v155
	v_pk_fma_f32 v[148:149], v[144:145], v[198:199], v[200:201]
	v_pk_fma_f32 v[156:157], v[152:153], v[198:199], v[200:201]
	v_pk_fma_f32 v[148:149], v[148:149], v[144:145], v[202:203]
	v_pk_fma_f32 v[156:157], v[156:157], v[152:153], v[202:203]
	v_pk_fma_f32 v[148:149], v[148:149], v[144:145], v[210:211]
	v_pk_fma_f32 v[156:157], v[156:157], v[152:153], v[210:211]
	v_pk_fma_f32 v[148:149], v[148:149], v[144:145], v[212:213]
	v_pk_fma_f32 v[156:157], v[156:157], v[152:153], v[212:213]
	v_pk_mul_f32 v[148:149], v[148:149], v[144:145]
	v_pk_mul_f32 v[156:157], v[156:157], v[152:153]
	v_max_f32_e32 v150, 0, v4
	v_max_f32_e32 v151, 0, v5
	v_max_f32_e32 v166, 0, v6
	v_max_f32_e32 v167, 0, v7
	v_pk_mul_f32 v[148:149], v[148:149], v[146:147]
	v_pk_mul_f32 v[156:157], v[156:157], v[154:155]
	v_fma_f32 v4, -|v4|, v148, v150
	v_fma_f32 v5, -|v5|, v149, v151
	v_fma_f32 v6, -|v6|, v156, v166
	v_fma_f32 v7, -|v7|, v157, v167
	v_pk_fma_f32 v[226:227], v[4:5], v[4:5], v[226:227]
	v_pk_fma_f32 v[226:227], v[6:7], v[6:7], v[226:227]
	v_cvt_pk_bf16_f32 v232, v4, v5
	v_cvt_pk_bf16_f32 v233, v6, v7
	v_fma_f32 v144, |v0|, v196, 1.0
	v_fma_f32 v145, |v1|, v196, 1.0
	v_fma_f32 v152, |v2|, v196, 1.0
	v_fma_f32 v153, |v3|, v196, 1.0
	v_pk_mul_f32 v[146:147], v[0:1], v[0:1]
	v_pk_mul_f32 v[154:155], v[2:3], v[2:3]
	v_rcp_f32_e32 v144, v144
	v_rcp_f32_e32 v145, v145
	v_rcp_f32_e32 v152, v152
	v_rcp_f32_e32 v153, v153
	v_pk_mul_f32 v[146:147], v[146:147], v[214:215]
	v_pk_mul_f32 v[154:155], v[154:155], v[214:215]
	v_exp_f32_e32 v146, v146
	v_exp_f32_e32 v147, v147
	v_exp_f32_e32 v154, v154
	v_exp_f32_e32 v155, v155
	v_pk_fma_f32 v[148:149], v[144:145], v[198:199], v[200:201]
	v_pk_fma_f32 v[156:157], v[152:153], v[198:199], v[200:201]
	v_pk_fma_f32 v[148:149], v[148:149], v[144:145], v[202:203]
	v_pk_fma_f32 v[156:157], v[156:157], v[152:153], v[202:203]
	v_pk_fma_f32 v[148:149], v[148:149], v[144:145], v[210:211]
	v_pk_fma_f32 v[156:157], v[156:157], v[152:153], v[210:211]
	v_pk_fma_f32 v[148:149], v[148:149], v[144:145], v[212:213]
	v_pk_fma_f32 v[156:157], v[156:157], v[152:153], v[212:213]
	v_pk_mul_f32 v[148:149], v[148:149], v[144:145]
	v_pk_mul_f32 v[156:157], v[156:157], v[152:153]
	v_max_f32_e32 v150, 0, v0
	v_max_f32_e32 v151, 0, v1
	v_max_f32_e32 v166, 0, v2
	v_max_f32_e32 v167, 0, v3
	v_pk_mul_f32 v[148:149], v[148:149], v[146:147]
	v_pk_mul_f32 v[156:157], v[156:157], v[154:155]
	v_fma_f32 v0, -|v0|, v148, v150
	v_fma_f32 v1, -|v1|, v149, v151
	v_fma_f32 v2, -|v2|, v156, v166
	v_fma_f32 v3, -|v3|, v157, v167
	v_pk_fma_f32 v[226:227], v[0:1], v[0:1], v[226:227]
	v_pk_fma_f32 v[226:227], v[2:3], v[2:3], v[226:227]
	v_cvt_pk_bf16_f32 v234, v0, v1
	v_cvt_pk_bf16_f32 v235, v2, v3
	buffer_store_dwordx4 v[232:235], v216, s[72:75], s2 offen offset:256
	v_add_f32_e32 v225, v226, v227
	s_cmp_ge_i32 s18, s58
	s_cselect_b64 s[2:3], -1, 0
	s_and_b64 s[2:3], s[2:3], s[22:23]
	s_and_b64 vcc, exec, s[2:3]
	s_cbranch_vccz .LBB0_509
	v_xor_b32_e32 v228, 16, v177
	v_xor_b32_e32 v229, 32, v177
	v_lshlrev_b32_e32 v228, 2, v228
	v_lshlrev_b32_e32 v229, 2, v229
	ds_bpermute_b32 v144, v228, v218
	ds_bpermute_b32 v145, v228, v219
	ds_bpermute_b32 v146, v228, v220
	ds_bpermute_b32 v147, v228, v221
	ds_bpermute_b32 v148, v228, v222
	ds_bpermute_b32 v149, v228, v223
	ds_bpermute_b32 v150, v228, v224
	ds_bpermute_b32 v151, v228, v225
	s_waitcnt lgkmcnt(0)
	v_add_f32_e32 v218, v218, v144
	v_add_f32_e32 v219, v219, v145
	v_add_f32_e32 v220, v220, v146
	v_add_f32_e32 v221, v221, v147
	v_add_f32_e32 v222, v222, v148
	v_add_f32_e32 v223, v223, v149
	v_add_f32_e32 v224, v224, v150
	v_add_f32_e32 v225, v225, v151
	ds_bpermute_b32 v144, v229, v218
	ds_bpermute_b32 v145, v229, v219
	ds_bpermute_b32 v146, v229, v220
	ds_bpermute_b32 v147, v229, v221
	ds_bpermute_b32 v148, v229, v222
	ds_bpermute_b32 v149, v229, v223
	ds_bpermute_b32 v150, v229, v224
	ds_bpermute_b32 v151, v229, v225
	s_sub_i32 s2, s18, s58
	s_lshl_b32 s2, s2, 2
	s_or_b32 s2, s2, s62
	s_ashr_i32 s3, s2, 31
	s_lshl_b64 s[2:3], s[2:3], 17
	s_add_u32 s2, s48, s2
	s_addc_u32 s3, s49, s3
	v_mov_b32_e32 v237, 0
	v_lshl_add_u64 v[230:231], v[236:237], 2, s[2:3]
	s_waitcnt lgkmcnt(0)
	v_add_f32_e32 v218, v218, v144
	v_add_f32_e32 v219, v219, v145
	v_add_f32_e32 v220, v220, v146
	v_add_f32_e32 v221, v221, v147
	v_add_f32_e32 v222, v222, v148
	v_add_f32_e32 v223, v223, v149
	v_add_f32_e32 v224, v224, v150
	v_add_f32_e32 v225, v225, v151
	s_mov_b64 exec, 0xffff
	global_store_dword v[230:231], v218, off
	global_store_dword v[230:231], v219, off offset:64
	global_store_dword v[230:231], v220, off offset:128
	global_store_dword v[230:231], v221, off offset:192
	global_store_dword v[230:231], v222, off offset:512
	global_store_dword v[230:231], v223, off offset:576
	global_store_dword v[230:231], v224, off offset:640
	global_store_dword v[230:231], v225, off offset:704
	s_mov_b64 exec, -1
	s_branch .LBB0_509
.Lepi_notgelu:
	s_cmp_lg_u32 s95, 2
	s_cbranch_scc1 .Lepi_generic
	s_or_b64 s[2:3], s[24:25], s[22:23]
	s_and_b64 vcc, exec, s[2:3]
	s_cbranch_vccnz .Lepi_generic
	s_and_b64 vcc, exec, s[26:27]
	s_cbranch_vccz .Lepi_generic
	v_lshl_add_u32 v156, s6, 8, v163
	s_lshl_b32 s2, s18, 8
	s_or_b32 s2, s2, s38
	v_or_b32_e32 v157, s2, v137
	v_mul_lo_u32 v156, v156, s33
	v_add_lshl_u32 v156, v156, v157, 1
	v_max_f32_e32 v124, 0, v124
	v_max_f32_e32 v125, 0, v125
	v_max_f32_e32 v126, 0, v126
	v_max_f32_e32 v127, 0, v127
	v_max_f32_e32 v120, 0, v120
	v_max_f32_e32 v121, 0, v121
	v_max_f32_e32 v122, 0, v122
	v_max_f32_e32 v123, 0, v123
	v_mul_f32_e32 v124, v124, v124
	v_mul_f32_e32 v125, v125, v125
	v_mul_f32_e32 v126, v126, v126
	v_mul_f32_e32 v127, v127, v127
	v_mul_f32_e32 v120, v120, v120
	v_mul_f32_e32 v121, v121, v121
	v_mul_f32_e32 v122, v122, v122
	v_mul_f32_e32 v123, v123, v123
	v_cvt_pk_bf16_f32 v144, v124, v125
	v_cvt_pk_bf16_f32 v145, v126, v127
	v_cvt_pk_bf16_f32 v146, v120, v121
	v_cvt_pk_bf16_f32 v147, v122, v123
	buffer_store_dwordx4 v[144:147], v156, s[72:75], 0 offen
	v_max_f32_e32 v116, 0, v116
	v_max_f32_e32 v117, 0, v117
	v_max_f32_e32 v118, 0, v118
	v_max_f32_e32 v119, 0, v119
	v_max_f32_e32 v112, 0, v112
	v_max_f32_e32 v113, 0, v113
	v_max_f32_e32 v114, 0, v114
	v_max_f32_e32 v115, 0, v115
	v_mul_f32_e32 v116, v116, v116
	v_mul_f32_e32 v117, v117, v117
	v_mul_f32_e32 v118, v118, v118
	v_mul_f32_e32 v119, v119, v119
	v_mul_f32_e32 v112, v112, v112
	v_mul_f32_e32 v113, v113, v113
	v_mul_f32_e32 v114, v114, v114
	v_mul_f32_e32 v115, v115, v115
	v_cvt_pk_bf16_f32 v152, v116, v117
	v_cvt_pk_bf16_f32 v153, v118, v119
	v_cvt_pk_bf16_f32 v154, v112, v113
	v_cvt_pk_bf16_f32 v155, v114, v115
	buffer_store_dwordx4 v[152:155], v156, s[72:75], 0 offen offset:256
	s_mul_i32 s2, s33, 0x20
	v_max_f32_e32 v108, 0, v108
	v_max_f32_e32 v109, 0, v109
	v_max_f32_e32 v110, 0, v110
	v_max_f32_e32 v111, 0, v111
	v_max_f32_e32 v104, 0, v104
	v_max_f32_e32 v105, 0, v105
	v_max_f32_e32 v106, 0, v106
	v_max_f32_e32 v107, 0, v107
	v_mul_f32_e32 v108, v108, v108
	v_mul_f32_e32 v109, v109, v109
	v_mul_f32_e32 v110, v110, v110
	v_mul_f32_e32 v111, v111, v111
	v_mul_f32_e32 v104, v104, v104
	v_mul_f32_e32 v105, v105, v105
	v_mul_f32_e32 v106, v106, v106
	v_mul_f32_e32 v107, v107, v107
	v_cvt_pk_bf16_f32 v144, v108, v109
	v_cvt_pk_bf16_f32 v145, v110, v111
	v_cvt_pk_bf16_f32 v146, v104, v105
	v_cvt_pk_bf16_f32 v147, v106, v107
	buffer_store_dwordx4 v[144:147], v156, s[72:75], s2 offen
	v_max_f32_e32 v100, 0, v100
	v_max_f32_e32 v101, 0, v101
	v_max_f32_e32 v102, 0, v102
	v_max_f32_e32 v103, 0, v103
	v_max_f32_e32 v96, 0, v96
	v_max_f32_e32 v97, 0, v97
	v_max_f32_e32 v98, 0, v98
	v_max_f32_e32 v99, 0, v99
	v_mul_f32_e32 v100, v100, v100
	v_mul_f32_e32 v101, v101, v101
	v_mul_f32_e32 v102, v102, v102
	v_mul_f32_e32 v103, v103, v103
	v_mul_f32_e32 v96, v96, v96
	v_mul_f32_e32 v97, v97, v97
	v_mul_f32_e32 v98, v98, v98
	v_mul_f32_e32 v99, v99, v99
	v_cvt_pk_bf16_f32 v152, v100, v101
	v_cvt_pk_bf16_f32 v153, v102, v103
	v_cvt_pk_bf16_f32 v154, v96, v97
	v_cvt_pk_bf16_f32 v155, v98, v99
	buffer_store_dwordx4 v[152:155], v156, s[72:75], s2 offen offset:256
	s_mul_i32 s2, s33, 0x40
	v_max_f32_e32 v92, 0, v92
	v_max_f32_e32 v93, 0, v93
	v_max_f32_e32 v94, 0, v94
	v_max_f32_e32 v95, 0, v95
	v_max_f32_e32 v88, 0, v88
	v_max_f32_e32 v89, 0, v89
	v_max_f32_e32 v90, 0, v90
	v_max_f32_e32 v91, 0, v91
	v_mul_f32_e32 v92, v92, v92
	v_mul_f32_e32 v93, v93, v93
	v_mul_f32_e32 v94, v94, v94
	v_mul_f32_e32 v95, v95, v95
	v_mul_f32_e32 v88, v88, v88
	v_mul_f32_e32 v89, v89, v89
	v_mul_f32_e32 v90, v90, v90
	v_mul_f32_e32 v91, v91, v91
	v_cvt_pk_bf16_f32 v144, v92, v93
	v_cvt_pk_bf16_f32 v145, v94, v95
	v_cvt_pk_bf16_f32 v146, v88, v89
	v_cvt_pk_bf16_f32 v147, v90, v91
	buffer_store_dwordx4 v[144:147], v156, s[72:75], s2 offen
	v_max_f32_e32 v84, 0, v84
	v_max_f32_e32 v85, 0, v85
	v_max_f32_e32 v86, 0, v86
	v_max_f32_e32 v87, 0, v87
	v_max_f32_e32 v80, 0, v80
	v_max_f32_e32 v81, 0, v81
	v_max_f32_e32 v82, 0, v82
	v_max_f32_e32 v83, 0, v83
	v_mul_f32_e32 v84, v84, v84
	v_mul_f32_e32 v85, v85, v85
	v_mul_f32_e32 v86, v86, v86
	v_mul_f32_e32 v87, v87, v87
	v_mul_f32_e32 v80, v80, v80
	v_mul_f32_e32 v81, v81, v81
	v_mul_f32_e32 v82, v82, v82
	v_mul_f32_e32 v83, v83, v83
	v_cvt_pk_bf16_f32 v152, v84, v85
	v_cvt_pk_bf16_f32 v153, v86, v87
	v_cvt_pk_bf16_f32 v154, v80, v81
	v_cvt_pk_bf16_f32 v155, v82, v83
	buffer_store_dwordx4 v[152:155], v156, s[72:75], s2 offen offset:256
	s_mul_i32 s2, s33, 0x60
	v_max_f32_e32 v76, 0, v76
	v_max_f32_e32 v77, 0, v77
	v_max_f32_e32 v78, 0, v78
	v_max_f32_e32 v79, 0, v79
	v_max_f32_e32 v72, 0, v72
	v_max_f32_e32 v73, 0, v73
	v_max_f32_e32 v74, 0, v74
	v_max_f32_e32 v75, 0, v75
	v_mul_f32_e32 v76, v76, v76
	v_mul_f32_e32 v77, v77, v77
	v_mul_f32_e32 v78, v78, v78
	v_mul_f32_e32 v79, v79, v79
	v_mul_f32_e32 v72, v72, v72
	v_mul_f32_e32 v73, v73, v73
	v_mul_f32_e32 v74, v74, v74
	v_mul_f32_e32 v75, v75, v75
	v_cvt_pk_bf16_f32 v144, v76, v77
	v_cvt_pk_bf16_f32 v145, v78, v79
	v_cvt_pk_bf16_f32 v146, v72, v73
	v_cvt_pk_bf16_f32 v147, v74, v75
	buffer_store_dwordx4 v[144:147], v156, s[72:75], s2 offen
	v_max_f32_e32 v68, 0, v68
	v_max_f32_e32 v69, 0, v69
	v_max_f32_e32 v70, 0, v70
	v_max_f32_e32 v71, 0, v71
	v_max_f32_e32 v64, 0, v64
	v_max_f32_e32 v65, 0, v65
	v_max_f32_e32 v66, 0, v66
	v_max_f32_e32 v67, 0, v67
	v_mul_f32_e32 v68, v68, v68
	v_mul_f32_e32 v69, v69, v69
	v_mul_f32_e32 v70, v70, v70
	v_mul_f32_e32 v71, v71, v71
	v_mul_f32_e32 v64, v64, v64
	v_mul_f32_e32 v65, v65, v65
	v_mul_f32_e32 v66, v66, v66
	v_mul_f32_e32 v67, v67, v67
	v_cvt_pk_bf16_f32 v152, v68, v69
	v_cvt_pk_bf16_f32 v153, v70, v71
	v_cvt_pk_bf16_f32 v154, v64, v65
	v_cvt_pk_bf16_f32 v155, v66, v67
	buffer_store_dwordx4 v[152:155], v156, s[72:75], s2 offen offset:256
	s_mul_i32 s2, s33, 0x100
	v_max_f32_e32 v60, 0, v60
	v_max_f32_e32 v61, 0, v61
	v_max_f32_e32 v62, 0, v62
	v_max_f32_e32 v63, 0, v63
	v_max_f32_e32 v56, 0, v56
	v_max_f32_e32 v57, 0, v57
	v_max_f32_e32 v58, 0, v58
	v_max_f32_e32 v59, 0, v59
	v_mul_f32_e32 v60, v60, v60
	v_mul_f32_e32 v61, v61, v61
	v_mul_f32_e32 v62, v62, v62
	v_mul_f32_e32 v63, v63, v63
	v_mul_f32_e32 v56, v56, v56
	v_mul_f32_e32 v57, v57, v57
	v_mul_f32_e32 v58, v58, v58
	v_mul_f32_e32 v59, v59, v59
	v_cvt_pk_bf16_f32 v144, v60, v61
	v_cvt_pk_bf16_f32 v145, v62, v63
	v_cvt_pk_bf16_f32 v146, v56, v57
	v_cvt_pk_bf16_f32 v147, v58, v59
	buffer_store_dwordx4 v[144:147], v156, s[72:75], s2 offen
	v_max_f32_e32 v52, 0, v52
	v_max_f32_e32 v53, 0, v53
	v_max_f32_e32 v54, 0, v54
	v_max_f32_e32 v55, 0, v55
	v_max_f32_e32 v48, 0, v48
	v_max_f32_e32 v49, 0, v49
	v_max_f32_e32 v50, 0, v50
	v_max_f32_e32 v51, 0, v51
	v_mul_f32_e32 v52, v52, v52
	v_mul_f32_e32 v53, v53, v53
	v_mul_f32_e32 v54, v54, v54
	v_mul_f32_e32 v55, v55, v55
	v_mul_f32_e32 v48, v48, v48
	v_mul_f32_e32 v49, v49, v49
	v_mul_f32_e32 v50, v50, v50
	v_mul_f32_e32 v51, v51, v51
	v_cvt_pk_bf16_f32 v152, v52, v53
	v_cvt_pk_bf16_f32 v153, v54, v55
	v_cvt_pk_bf16_f32 v154, v48, v49
	v_cvt_pk_bf16_f32 v155, v50, v51
	buffer_store_dwordx4 v[152:155], v156, s[72:75], s2 offen offset:256
	s_mul_i32 s2, s33, 0x120
	v_max_f32_e32 v44, 0, v44
	v_max_f32_e32 v45, 0, v45
	v_max_f32_e32 v46, 0, v46
	v_max_f32_e32 v47, 0, v47
	v_max_f32_e32 v40, 0, v40
	v_max_f32_e32 v41, 0, v41
	v_max_f32_e32 v42, 0, v42
	v_max_f32_e32 v43, 0, v43
	v_mul_f32_e32 v44, v44, v44
	v_mul_f32_e32 v45, v45, v45
	v_mul_f32_e32 v46, v46, v46
	v_mul_f32_e32 v47, v47, v47
	v_mul_f32_e32 v40, v40, v40
	v_mul_f32_e32 v41, v41, v41
	v_mul_f32_e32 v42, v42, v42
	v_mul_f32_e32 v43, v43, v43
	v_cvt_pk_bf16_f32 v144, v44, v45
	v_cvt_pk_bf16_f32 v145, v46, v47
	v_cvt_pk_bf16_f32 v146, v40, v41
	v_cvt_pk_bf16_f32 v147, v42, v43
	buffer_store_dwordx4 v[144:147], v156, s[72:75], s2 offen
	v_max_f32_e32 v36, 0, v36
	v_max_f32_e32 v37, 0, v37
	v_max_f32_e32 v38, 0, v38
	v_max_f32_e32 v39, 0, v39
	v_max_f32_e32 v32, 0, v32
	v_max_f32_e32 v33, 0, v33
	v_max_f32_e32 v34, 0, v34
	v_max_f32_e32 v35, 0, v35
	v_mul_f32_e32 v36, v36, v36
	v_mul_f32_e32 v37, v37, v37
	v_mul_f32_e32 v38, v38, v38
	v_mul_f32_e32 v39, v39, v39
	v_mul_f32_e32 v32, v32, v32
	v_mul_f32_e32 v33, v33, v33
	v_mul_f32_e32 v34, v34, v34
	v_mul_f32_e32 v35, v35, v35
	v_cvt_pk_bf16_f32 v152, v36, v37
	v_cvt_pk_bf16_f32 v153, v38, v39
	v_cvt_pk_bf16_f32 v154, v32, v33
	v_cvt_pk_bf16_f32 v155, v34, v35
	buffer_store_dwordx4 v[152:155], v156, s[72:75], s2 offen offset:256
	s_mul_i32 s2, s33, 0x140
	v_max_f32_e32 v28, 0, v28
	v_max_f32_e32 v29, 0, v29
	v_max_f32_e32 v30, 0, v30
	v_max_f32_e32 v31, 0, v31
	v_max_f32_e32 v24, 0, v24
	v_max_f32_e32 v25, 0, v25
	v_max_f32_e32 v26, 0, v26
	v_max_f32_e32 v27, 0, v27
	v_mul_f32_e32 v28, v28, v28
	v_mul_f32_e32 v29, v29, v29
	v_mul_f32_e32 v30, v30, v30
	v_mul_f32_e32 v31, v31, v31
	v_mul_f32_e32 v24, v24, v24
	v_mul_f32_e32 v25, v25, v25
	v_mul_f32_e32 v26, v26, v26
	v_mul_f32_e32 v27, v27, v27
	v_cvt_pk_bf16_f32 v144, v28, v29
	v_cvt_pk_bf16_f32 v145, v30, v31
	v_cvt_pk_bf16_f32 v146, v24, v25
	v_cvt_pk_bf16_f32 v147, v26, v27
	buffer_store_dwordx4 v[144:147], v156, s[72:75], s2 offen
	v_max_f32_e32 v20, 0, v20
	v_max_f32_e32 v21, 0, v21
	v_max_f32_e32 v22, 0, v22
	v_max_f32_e32 v23, 0, v23
	v_max_f32_e32 v16, 0, v16
	v_max_f32_e32 v17, 0, v17
	v_max_f32_e32 v18, 0, v18
	v_max_f32_e32 v19, 0, v19
	v_mul_f32_e32 v20, v20, v20
	v_mul_f32_e32 v21, v21, v21
	v_mul_f32_e32 v22, v22, v22
	v_mul_f32_e32 v23, v23, v23
	v_mul_f32_e32 v16, v16, v16
	v_mul_f32_e32 v17, v17, v17
	v_mul_f32_e32 v18, v18, v18
	v_mul_f32_e32 v19, v19, v19
	v_cvt_pk_bf16_f32 v152, v20, v21
	v_cvt_pk_bf16_f32 v153, v22, v23
	v_cvt_pk_bf16_f32 v154, v16, v17
	v_cvt_pk_bf16_f32 v155, v18, v19
	buffer_store_dwordx4 v[152:155], v156, s[72:75], s2 offen offset:256
	s_mul_i32 s2, s33, 0x160
	v_max_f32_e32 v12, 0, v12
	v_max_f32_e32 v13, 0, v13
	v_max_f32_e32 v14, 0, v14
	v_max_f32_e32 v15, 0, v15
	v_max_f32_e32 v8, 0, v8
	v_max_f32_e32 v9, 0, v9
	v_max_f32_e32 v10, 0, v10
	v_max_f32_e32 v11, 0, v11
	v_mul_f32_e32 v12, v12, v12
	v_mul_f32_e32 v13, v13, v13
	v_mul_f32_e32 v14, v14, v14
	v_mul_f32_e32 v15, v15, v15
	v_mul_f32_e32 v8, v8, v8
	v_mul_f32_e32 v9, v9, v9
	v_mul_f32_e32 v10, v10, v10
	v_mul_f32_e32 v11, v11, v11
	v_cvt_pk_bf16_f32 v144, v12, v13
	v_cvt_pk_bf16_f32 v145, v14, v15
	v_cvt_pk_bf16_f32 v146, v8, v9
	v_cvt_pk_bf16_f32 v147, v10, v11
	buffer_store_dwordx4 v[144:147], v156, s[72:75], s2 offen
	v_max_f32_e32 v4, 0, v4
	v_max_f32_e32 v5, 0, v5
	v_max_f32_e32 v6, 0, v6
	v_max_f32_e32 v7, 0, v7
	v_max_f32_e32 v0, 0, v0
	v_max_f32_e32 v1, 0, v1
	v_max_f32_e32 v2, 0, v2
	v_max_f32_e32 v3, 0, v3
	v_mul_f32_e32 v4, v4, v4
	v_mul_f32_e32 v5, v5, v5
	v_mul_f32_e32 v6, v6, v6
	v_mul_f32_e32 v7, v7, v7
	v_mul_f32_e32 v0, v0, v0
	v_mul_f32_e32 v1, v1, v1
	v_mul_f32_e32 v2, v2, v2
	v_mul_f32_e32 v3, v3, v3
	v_cvt_pk_bf16_f32 v152, v4, v5
	v_cvt_pk_bf16_f32 v153, v6, v7
	v_cvt_pk_bf16_f32 v154, v0, v1
	v_cvt_pk_bf16_f32 v155, v2, v3
	buffer_store_dwordx4 v[152:155], v156, s[72:75], s2 offen offset:256
	s_branch .LBB0_509
